# FFN-up / projection epilogues: RMS scales computed once per phase and read back from LDS, so tile epilogues no longer drain the next tile's LDS-DMA prefetch behind vmcnt(0)
# speedup vs baseline: 1.0072x; 1.0072x over previous
.LBB0_228:
	s_add_u32 s8, s66, 0xea78400
	s_addc_u32 s9, s67, 0
	s_and_b32 s12, s10, 3
	s_add_i32 m0, s31, 0x18000
	v_lshl_add_u64 v[8:9], v[8:9], 0, s[80:81]
	s_lshl_b32 s13, s5, 13
	s_lshl_b32 s14, s12, 12
	s_waitcnt vmcnt(2)
	s_barrier
	global_load_lds_dwordx4 v[8:9], off
	v_lshl_add_u64 v[6:7], v[6:7], 0, s[80:81]
	s_add_i32 m0, s31, 0x1a000
	s_add_i32 s37, s31, 0x8000
	s_add_i32 s38, s31, 0xa000
	global_load_lds_dwordx4 v[6:7], off
	v_lshl_add_u64 v[2:3], v[2:3], 0, s[80:81]
	s_mov_b32 m0, s37
	s_add_u32 s10, s22, 0x40080
	global_load_lds_dwordx4 v[2:3], off
	v_lshl_add_u64 v[2:3], v[4:5], 0, s[80:81]
	s_mov_b32 m0, s38
	s_addc_u32 s11, s23, 0
	global_load_lds_dwordx4 v[2:3], off
	s_add_i32 m0, s31, 0x1c000
	v_lshl_add_u64 v[2:3], s[10:11], 0, v[0:1]
	global_load_lds_dwordx4 v[2:3], off
	v_lshl_add_u64 v[2:3], s[10:11], 0, v[130:131]
	s_add_i32 m0, s31, 0x1e000
	s_cmpk_lt_u32 s4, 0x100
	global_load_lds_dwordx4 v[2:3], off
	v_bfe_u32 v3, v10, 4, 2
	v_and_b32_e32 v2, 15, v10
	v_lshlrev_b32_e32 v4, 4, v3
	v_lshl_or_b32 v145, s5, 6, v2
	v_lshl_or_b32 v2, v2, 6, v4
	v_lshlrev_b32_e32 v4, 2, v10
	v_and_b32_e32 v4, 32, v4
	v_bitop3_b32 v5, v2, s13, v4 bitop3:0xde
	v_bitop3_b32 v160, v2, s14, v4 bitop3:0xde
	v_lshlrev_b32_e32 v2, 2, v3
	v_lshl_or_b32 v162, s12, 4, v2
	v_lshlrev_b32_e32 v2, 14, v15
	v_and_b32_e32 v2, 0xffff8000, v2
	v_lshl_add_u32 v2, v14, 11, v2
	v_and_b32_e32 v3, 1, v15
	v_lshl_or_b32 v2, v3, 6, v2
	v_lshl_add_u32 v136, v16, 1, v2
	v_lshlrev_b32_e32 v2, 14, v11
	v_and_b32_e32 v2, 0xffff8000, v2
	s_waitcnt vmcnt(6)
	v_lshl_add_u32 v2, v12, 11, v2
	v_and_b32_e32 v3, 1, v11
	v_lshl_or_b32 v2, v3, 6, v2
	v_readlane_b32 s4, v250, 8
	s_cselect_b64 s[10:11], -1, 0
	v_mov_b32_e32 v137, v1
	v_lshl_add_u32 v138, v13, 1, v2
	v_mov_b32_e32 v139, v1
	s_mov_b32 s39, 0
	v_add_u32_e32 v163, 0, v5
	v_readlane_b32 s40, v250, 7
	s_mov_b32 s41, s4
	s_barrier
	v_readlane_b32 s5, v250, 9
	v_lshl_add_u32 v140, s41, 8, v145
	v_ashrrev_i32_e32 v141, 31, v140
	v_lshlrev_b64 v[164:165], 6, v[140:141]
	v_lshl_add_u64 v[164:165], s[66:67], 0, v[164:165]
	v_and_b32_e32 v166, 48, v197
	v_mov_b32_e32 v167, 0
	v_lshl_add_u64 v[164:165], v[164:165], 0, v[166:167]
	v_mov_b32_e32 v142, 0x2000
	v_mov_b32_e32 v143, 0
	v_lshl_add_u64 v[166:167], v[164:165], 0, v[142:143]
	global_load_dwordx4 v[204:207], v[164:165], off
	global_load_dwordx4 v[208:211], v[164:165], off offset:1024
	global_load_dwordx4 v[212:215], v[164:165], off offset:2048
	global_load_dwordx4 v[216:219], v[164:165], off offset:3072
	global_load_dwordx4 v[220:223], v[166:167], off
	global_load_dwordx4 v[224:227], v[166:167], off offset:1024
	global_load_dwordx4 v[228:231], v[166:167], off offset:2048
	global_load_dwordx4 v[232:235], v[166:167], off offset:3072
	v_lshlrev_b32_e32 v140, 5, v145
	v_add_u32_e32 v140, 0x20000, v140
	s_waitcnt vmcnt(0)
	v_add_f32_e32 v204, v204, v205
	v_add_f32_e32 v206, v206, v207
	v_add_f32_e32 v204, v204, v206
	v_mov_b32_e32 v205, v204
	s_nop 1
	v_permlane16_swap_b32_e32 v204, v205
	v_add_f32_e32 v204, v204, v205
	v_mov_b32_e32 v205, v204
	s_nop 1
	v_permlane32_swap_b32_e32 v204, v205
	v_add_f32_e32 v204, v204, v205
	v_fmamk_f32 v204, v204, 0x3a800000, v161
	v_cmp_gt_f32_e32 vcc, s62, v204
	v_mul_f32_e32 v205, 0x4b800000, v204
	s_nop 0
	v_cndmask_b32_e32 v204, v204, v205, vcc
	v_rsq_f32_e32 v204, v204
	s_nop 0
	v_mul_f32_e32 v205, 0x45800000, v204
	v_cndmask_b32_e32 v204, v204, v205, vcc
	v_add_f32_e32 v208, v208, v209
	v_add_f32_e32 v210, v210, v211
	v_add_f32_e32 v208, v208, v210
	v_mov_b32_e32 v209, v208
	s_nop 1
	v_permlane16_swap_b32_e32 v208, v209
	v_add_f32_e32 v208, v208, v209
	v_mov_b32_e32 v209, v208
	s_nop 1
	v_permlane32_swap_b32_e32 v208, v209
	v_add_f32_e32 v208, v208, v209
	v_fmamk_f32 v208, v208, 0x3a800000, v161
	v_cmp_gt_f32_e32 vcc, s62, v208
	v_mul_f32_e32 v209, 0x4b800000, v208
	s_nop 0
	v_cndmask_b32_e32 v208, v208, v209, vcc
	v_rsq_f32_e32 v208, v208
	s_nop 0
	v_mul_f32_e32 v209, 0x45800000, v208
	v_cndmask_b32_e32 v208, v208, v209, vcc
	v_add_f32_e32 v212, v212, v213
	v_add_f32_e32 v214, v214, v215
	v_add_f32_e32 v212, v212, v214
	v_mov_b32_e32 v213, v212
	s_nop 1
	v_permlane16_swap_b32_e32 v212, v213
	v_add_f32_e32 v212, v212, v213
	v_mov_b32_e32 v213, v212
	s_nop 1
	v_permlane32_swap_b32_e32 v212, v213
	v_add_f32_e32 v212, v212, v213
	v_fmamk_f32 v212, v212, 0x3a800000, v161
	v_cmp_gt_f32_e32 vcc, s62, v212
	v_mul_f32_e32 v213, 0x4b800000, v212
	s_nop 0
	v_cndmask_b32_e32 v212, v212, v213, vcc
	v_rsq_f32_e32 v212, v212
	s_nop 0
	v_mul_f32_e32 v213, 0x45800000, v212
	v_cndmask_b32_e32 v212, v212, v213, vcc
	v_add_f32_e32 v216, v216, v217
	v_add_f32_e32 v218, v218, v219
	v_add_f32_e32 v216, v216, v218
	v_mov_b32_e32 v217, v216
	s_nop 1
	v_permlane16_swap_b32_e32 v216, v217
	v_add_f32_e32 v216, v216, v217
	v_mov_b32_e32 v217, v216
	s_nop 1
	v_permlane32_swap_b32_e32 v216, v217
	v_add_f32_e32 v216, v216, v217
	v_fmamk_f32 v216, v216, 0x3a800000, v161
	v_cmp_gt_f32_e32 vcc, s62, v216
	v_mul_f32_e32 v217, 0x4b800000, v216
	s_nop 0
	v_cndmask_b32_e32 v216, v216, v217, vcc
	v_rsq_f32_e32 v216, v216
	s_nop 0
	v_mul_f32_e32 v217, 0x45800000, v216
	v_cndmask_b32_e32 v216, v216, v217, vcc
	v_add_f32_e32 v220, v220, v221
	v_add_f32_e32 v222, v222, v223
	v_add_f32_e32 v220, v220, v222
	v_mov_b32_e32 v221, v220
	s_nop 1
	v_permlane16_swap_b32_e32 v220, v221
	v_add_f32_e32 v220, v220, v221
	v_mov_b32_e32 v221, v220
	s_nop 1
	v_permlane32_swap_b32_e32 v220, v221
	v_add_f32_e32 v220, v220, v221
	v_fmamk_f32 v220, v220, 0x3a800000, v161
	v_cmp_gt_f32_e32 vcc, s62, v220
	v_mul_f32_e32 v221, 0x4b800000, v220
	s_nop 0
	v_cndmask_b32_e32 v220, v220, v221, vcc
	v_rsq_f32_e32 v220, v220
	s_nop 0
	v_mul_f32_e32 v221, 0x45800000, v220
	v_cndmask_b32_e32 v220, v220, v221, vcc
	v_add_f32_e32 v224, v224, v225
	v_add_f32_e32 v226, v226, v227
	v_add_f32_e32 v224, v224, v226
	v_mov_b32_e32 v225, v224
	s_nop 1
	v_permlane16_swap_b32_e32 v224, v225
	v_add_f32_e32 v224, v224, v225
	v_mov_b32_e32 v225, v224
	s_nop 1
	v_permlane32_swap_b32_e32 v224, v225
	v_add_f32_e32 v224, v224, v225
	v_fmamk_f32 v224, v224, 0x3a800000, v161
	v_cmp_gt_f32_e32 vcc, s62, v224
	v_mul_f32_e32 v225, 0x4b800000, v224
	s_nop 0
	v_cndmask_b32_e32 v224, v224, v225, vcc
	v_rsq_f32_e32 v224, v224
	s_nop 0
	v_mul_f32_e32 v225, 0x45800000, v224
	v_cndmask_b32_e32 v224, v224, v225, vcc
	v_add_f32_e32 v228, v228, v229
	v_add_f32_e32 v230, v230, v231
	v_add_f32_e32 v228, v228, v230
	v_mov_b32_e32 v229, v228
	s_nop 1
	v_permlane16_swap_b32_e32 v228, v229
	v_add_f32_e32 v228, v228, v229
	v_mov_b32_e32 v229, v228
	s_nop 1
	v_permlane32_swap_b32_e32 v228, v229
	v_add_f32_e32 v228, v228, v229
	v_fmamk_f32 v228, v228, 0x3a800000, v161
	v_cmp_gt_f32_e32 vcc, s62, v228
	v_mul_f32_e32 v229, 0x4b800000, v228
	s_nop 0
	v_cndmask_b32_e32 v228, v228, v229, vcc
	v_rsq_f32_e32 v228, v228
	s_nop 0
	v_mul_f32_e32 v229, 0x45800000, v228
	v_cndmask_b32_e32 v228, v228, v229, vcc
	v_add_f32_e32 v232, v232, v233
	v_add_f32_e32 v234, v234, v235
	v_add_f32_e32 v232, v232, v234
	v_mov_b32_e32 v233, v232
	s_nop 1
	v_permlane16_swap_b32_e32 v232, v233
	v_add_f32_e32 v232, v232, v233
	v_mov_b32_e32 v233, v232
	s_nop 1
	v_permlane32_swap_b32_e32 v232, v233
	v_add_f32_e32 v232, v232, v233
	v_fmamk_f32 v232, v232, 0x3a800000, v161
	v_cmp_gt_f32_e32 vcc, s62, v232
	v_mul_f32_e32 v233, 0x4b800000, v232
	s_nop 0
	v_cndmask_b32_e32 v232, v232, v233, vcc
	v_rsq_f32_e32 v232, v232
	s_nop 0
	v_mul_f32_e32 v233, 0x45800000, v232
	v_cndmask_b32_e32 v232, v232, v233, vcc
	ds_write_b32 v140, v204
	ds_write_b32 v140, v208 offset:4
	ds_write_b32 v140, v212 offset:8
	ds_write_b32 v140, v216 offset:12
	ds_write_b32 v140, v220 offset:16
	ds_write_b32 v140, v224 offset:20
	ds_write_b32 v140, v228 offset:24
	ds_write_b32 v140, v232 offset:28
	s_waitcnt lgkmcnt(0)
	s_branch .LBB0_231

.LBB0_237:
	v_bfe_u32 v246, v197, 4, 1
	v_mul_u32_u24_e32 v246, 0x15ff8, v246
	v_mov_b32_e32 v247, 0
	v_lshl_add_u32 v140, s41, 8, v145
	v_ashrrev_i32_e32 v141, 31, v140
	v_lshlrev_b64 v[164:165], 6, v[140:141]
	v_lshl_add_u64 v[164:165], s[66:67], 0, v[164:165]
	v_and_b32_e32 v166, 48, v197
	v_mov_b32_e32 v167, 0
	v_lshl_add_u64 v[164:165], v[164:165], 0, v[166:167]
	s_mov_b64 s[20:21], 0x2000
	v_lshl_add_u64 v[166:167], v[164:165], 0, s[20:21]
	v_lshl_or_b32 v142, s40, 7, v162
	v_ashrrev_i32_e32 v143, 31, v142
	v_lshlrev_b32_e32 v212, 5, v145
	v_add_u32_e32 v212, 0x20000, v212
	ds_read_b128 v[204:207], v212
	ds_read_b128 v[208:211], v212 offset:16
	s_waitcnt lgkmcnt(0)
	v_mov_b32_e32 v144, v204
	v_pk_mul_f32 v[126:127], v[126:127], v[144:145] op_sel_hi:[1,0]
	v_pk_mul_f32 v[122:123], v[122:123], v[144:145] op_sel_hi:[1,0]
	v_mul_f32_e32 v141, 0xbfb8aa3b, v126
	v_exp_f32_e32 v141, v141
	v_pk_mul_f32 v[124:125], v[124:125], v[144:145] op_sel_hi:[1,0]
	v_pk_mul_f32 v[118:119], v[118:119], v[144:145] op_sel_hi:[1,0]
	v_pk_mul_f32 v[114:115], v[114:115], v[144:145] op_sel_hi:[1,0]
	v_add_f32_e32 v141, 1.0, v141
	v_rcp_f32_e32 v164, v141
	v_mul_f32_e32 v141, 0xbfb8aa3b, v127
	v_exp_f32_e32 v141, v141
	v_pk_mul_f32 v[116:117], v[116:117], v[144:145] op_sel_hi:[1,0]
	v_add_f32_e32 v141, 1.0, v141
	v_rcp_f32_e32 v165, v141
	s_nop 0
	v_pk_mul_f32 v[126:127], v[126:127], v[164:165]
	s_nop 0
	v_pk_mul_f32 v[122:123], v[122:123], v[126:127]
	v_pk_mul_f32 v[126:127], v[128:129], v[144:145] op_sel_hi:[1,0]
	s_nop 0
	v_mul_f32_e32 v128, 0xbfb8aa3b, v126
	v_mul_f32_e32 v129, 0xbfb8aa3b, v127
	v_exp_f32_e32 v128, v128
	v_exp_f32_e32 v129, v129
	v_add_f32_e32 v128, 1.0, v128
	v_add_f32_e32 v129, 1.0, v129
	v_rcp_f32_e32 v128, v128
	v_rcp_f32_e32 v129, v129
	s_nop 0
	v_pk_mul_f32 v[126:127], v[126:127], v[128:129]
	s_nop 0
	v_pk_mul_f32 v[124:125], v[124:125], v[126:127]
	v_cvt_pk_bf16_f32 v126, v122, v123
	v_mov_b64_e32 v[122:123], s[8:9]
	v_cvt_pk_bf16_f32 v127, v124, v125
	v_mad_i64_i32 v[128:129], s[20:21], v140, s1, v[122:123]
	v_lshlrev_b64 v[124:125], 1, v[142:143]
	v_lshl_add_u64 v[128:129], v[128:129], 0, v[124:125]
	v_lshl_add_u64 v[244:245], v[128:129], 0, v[246:247]
	v_mov_b32_e32 v236, v126
	v_mov_b32_e32 v237, v127
	v_mul_f32_e32 v126, 0xbfb8aa3b, v118
	v_mul_f32_e32 v127, 0xbfb8aa3b, v119
	v_exp_f32_e32 v126, v126
	v_exp_f32_e32 v127, v127
	v_add_f32_e32 v126, 1.0, v126
	v_add_f32_e32 v127, 1.0, v127
	v_rcp_f32_e32 v126, v126
	v_rcp_f32_e32 v127, v127
	s_nop 0
	v_pk_mul_f32 v[118:119], v[118:119], v[126:127]
	s_nop 0
	v_pk_mul_f32 v[114:115], v[114:115], v[118:119]
	v_pk_mul_f32 v[118:119], v[120:121], v[144:145] op_sel_hi:[1,0]
	v_or_b32_e32 v126, 16, v140
	v_mul_f32_e32 v120, 0xbfb8aa3b, v118
	v_mul_f32_e32 v121, 0xbfb8aa3b, v119
	v_exp_f32_e32 v120, v120
	v_exp_f32_e32 v121, v121
	v_cvt_pk_bf16_f32 v114, v114, v115
	v_ashrrev_i32_e32 v127, 31, v126
	v_add_f32_e32 v120, 1.0, v120
	v_add_f32_e32 v121, 1.0, v121
	v_rcp_f32_e32 v120, v120
	v_rcp_f32_e32 v121, v121
	s_nop 0
	v_pk_mul_f32 v[118:119], v[118:119], v[120:121]
	s_nop 0
	v_pk_mul_f32 v[116:117], v[116:117], v[118:119]
	s_nop 0
	v_cvt_pk_bf16_f32 v115, v116, v117
	v_mov_b32_e32 v240, v114
	v_mov_b32_e32 v241, v115
	v_mov_b32_e32 v114, v205
	v_pk_mul_f32 v[110:111], v[110:111], v[114:115] op_sel_hi:[1,0]
	s_nop 0
	v_mul_f32_e32 v115, 0xbfb8aa3b, v110
	v_exp_f32_e32 v115, v115
	s_nop 0
	v_add_f32_e32 v115, 1.0, v115
	v_rcp_f32_e32 v116, v115
	v_mul_f32_e32 v115, 0xbfb8aa3b, v111
	v_exp_f32_e32 v115, v115
	s_nop 0
	v_add_f32_e32 v115, 1.0, v115
	v_rcp_f32_e32 v117, v115
	v_pk_mul_f32 v[106:107], v[106:107], v[114:115] op_sel_hi:[1,0]
	v_pk_mul_f32 v[108:109], v[108:109], v[114:115] op_sel_hi:[1,0]
	v_pk_mul_f32 v[102:103], v[102:103], v[114:115] op_sel_hi:[1,0]
	v_pk_mul_f32 v[110:111], v[110:111], v[116:117]
	v_pk_mul_f32 v[98:99], v[98:99], v[114:115] op_sel_hi:[1,0]
	v_pk_mul_f32 v[106:107], v[106:107], v[110:111]
	v_pk_mul_f32 v[110:111], v[112:113], v[114:115] op_sel_hi:[1,0]
	v_cvt_pk_bf16_f32 v106, v106, v107
	v_mul_f32_e32 v112, 0xbfb8aa3b, v110
	v_mul_f32_e32 v113, 0xbfb8aa3b, v111
	v_exp_f32_e32 v112, v112
	v_exp_f32_e32 v113, v113
	v_pk_mul_f32 v[100:101], v[100:101], v[114:115] op_sel_hi:[1,0]
	v_add_f32_e32 v112, 1.0, v112
	v_add_f32_e32 v113, 1.0, v113
	v_rcp_f32_e32 v112, v112
	v_rcp_f32_e32 v113, v113
	s_nop 0
	v_pk_mul_f32 v[110:111], v[110:111], v[112:113]
	s_nop 0
	v_pk_mul_f32 v[108:109], v[108:109], v[110:111]
	s_nop 0
	v_cvt_pk_bf16_f32 v107, v108, v109
	v_mad_i64_i32 v[108:109], s[20:21], v126, s1, v[122:123]
	v_lshl_add_u64 v[108:109], v[108:109], 0, v[124:125]
	v_mov_b32_e32 v238, v106
	v_mov_b32_e32 v239, v107
	s_nop 1
	v_permlane16_swap_b32_e32 v236, v238
	v_permlane16_swap_b32_e32 v237, v239
	global_store_dwordx4 v[244:245], v[236:239], off
	v_mul_f32_e32 v106, 0xbfb8aa3b, v102
	v_mul_f32_e32 v107, 0xbfb8aa3b, v103
	v_exp_f32_e32 v106, v106
	v_exp_f32_e32 v107, v107
	v_add_f32_e32 v106, 1.0, v106
	v_add_f32_e32 v107, 1.0, v107
	v_rcp_f32_e32 v106, v106
	v_rcp_f32_e32 v107, v107
	s_nop 0
	v_pk_mul_f32 v[102:103], v[102:103], v[106:107]
	s_nop 0
	v_pk_mul_f32 v[98:99], v[98:99], v[102:103]
	v_pk_mul_f32 v[102:103], v[104:105], v[114:115] op_sel_hi:[1,0]
	v_or_b32_e32 v106, 32, v140
	v_mul_f32_e32 v104, 0xbfb8aa3b, v102
	v_mul_f32_e32 v105, 0xbfb8aa3b, v103
	v_exp_f32_e32 v104, v104
	v_exp_f32_e32 v105, v105
	v_cvt_pk_bf16_f32 v98, v98, v99
	v_ashrrev_i32_e32 v107, 31, v106
	v_add_f32_e32 v104, 1.0, v104
	v_add_f32_e32 v105, 1.0, v105
	v_rcp_f32_e32 v104, v104
	v_rcp_f32_e32 v105, v105
	s_nop 0
	v_pk_mul_f32 v[102:103], v[102:103], v[104:105]
	s_nop 0
	v_pk_mul_f32 v[100:101], v[100:101], v[102:103]
	s_nop 0
	v_cvt_pk_bf16_f32 v99, v100, v101
	v_mov_b32_e32 v242, v98
	v_mov_b32_e32 v243, v99
	s_nop 1
	v_permlane16_swap_b32_e32 v240, v242
	v_permlane16_swap_b32_e32 v241, v243
	global_store_dwordx4 v[244:245], v[240:243], off offset:128
	v_mov_b32_e32 v98, v206
	v_pk_mul_f32 v[94:95], v[94:95], v[98:99] op_sel_hi:[1,0]
	s_nop 0
	v_mul_f32_e32 v99, 0xbfb8aa3b, v94
	v_exp_f32_e32 v99, v99
	s_nop 0
	v_add_f32_e32 v99, 1.0, v99
	v_rcp_f32_e32 v100, v99
	v_mul_f32_e32 v99, 0xbfb8aa3b, v95
	v_exp_f32_e32 v99, v99
	s_nop 0
	v_add_f32_e32 v99, 1.0, v99
	v_rcp_f32_e32 v101, v99
	v_pk_mul_f32 v[90:91], v[90:91], v[98:99] op_sel_hi:[1,0]
	v_pk_mul_f32 v[92:93], v[92:93], v[98:99] op_sel_hi:[1,0]
	v_pk_mul_f32 v[86:87], v[86:87], v[98:99] op_sel_hi:[1,0]
	v_pk_mul_f32 v[94:95], v[94:95], v[100:101]
	v_pk_mul_f32 v[82:83], v[82:83], v[98:99] op_sel_hi:[1,0]
	v_pk_mul_f32 v[90:91], v[90:91], v[94:95]
	v_pk_mul_f32 v[94:95], v[96:97], v[98:99] op_sel_hi:[1,0]
	v_cvt_pk_bf16_f32 v90, v90, v91
	v_mul_f32_e32 v96, 0xbfb8aa3b, v94
	v_mul_f32_e32 v97, 0xbfb8aa3b, v95
	v_exp_f32_e32 v96, v96
	v_exp_f32_e32 v97, v97
	v_pk_mul_f32 v[84:85], v[84:85], v[98:99] op_sel_hi:[1,0]
	v_add_f32_e32 v96, 1.0, v96
	v_add_f32_e32 v97, 1.0, v97
	v_rcp_f32_e32 v96, v96
	v_rcp_f32_e32 v97, v97
	s_nop 0
	v_pk_mul_f32 v[94:95], v[94:95], v[96:97]
	s_nop 0
	v_pk_mul_f32 v[92:93], v[92:93], v[94:95]
	s_nop 0
	v_cvt_pk_bf16_f32 v91, v92, v93
	v_mad_i64_i32 v[92:93], s[20:21], v106, s1, v[122:123]
	v_lshl_add_u64 v[92:93], v[92:93], 0, v[124:125]
	v_lshl_add_u64 v[244:245], v[92:93], 0, v[246:247]
	v_mov_b32_e32 v236, v90
	v_mov_b32_e32 v237, v91
	v_mul_f32_e32 v90, 0xbfb8aa3b, v86
	v_mul_f32_e32 v91, 0xbfb8aa3b, v87
	v_exp_f32_e32 v90, v90
	v_exp_f32_e32 v91, v91
	v_add_f32_e32 v90, 1.0, v90
	v_add_f32_e32 v91, 1.0, v91
	v_rcp_f32_e32 v90, v90
	v_rcp_f32_e32 v91, v91
	s_nop 0
	v_pk_mul_f32 v[86:87], v[86:87], v[90:91]
	s_nop 0
	v_pk_mul_f32 v[82:83], v[82:83], v[86:87]
	v_pk_mul_f32 v[86:87], v[88:89], v[98:99] op_sel_hi:[1,0]
	v_or_b32_e32 v90, 48, v140
	v_mul_f32_e32 v88, 0xbfb8aa3b, v86
	v_mul_f32_e32 v89, 0xbfb8aa3b, v87
	v_exp_f32_e32 v88, v88
	v_exp_f32_e32 v89, v89
	v_cvt_pk_bf16_f32 v82, v82, v83
	v_ashrrev_i32_e32 v91, 31, v90
	v_add_f32_e32 v88, 1.0, v88
	v_add_f32_e32 v89, 1.0, v89
	v_rcp_f32_e32 v88, v88
	v_rcp_f32_e32 v89, v89
	s_nop 0
	v_pk_mul_f32 v[86:87], v[86:87], v[88:89]
	s_nop 0
	v_pk_mul_f32 v[84:85], v[84:85], v[86:87]
	s_nop 0
	v_cvt_pk_bf16_f32 v83, v84, v85
	v_mov_b32_e32 v240, v82
	v_mov_b32_e32 v241, v83
	v_mov_b32_e32 v82, v207
	v_pk_mul_f32 v[78:79], v[78:79], v[82:83] op_sel_hi:[1,0]
	s_nop 0
	v_mul_f32_e32 v83, 0xbfb8aa3b, v78
	v_exp_f32_e32 v83, v83
	s_nop 0
	v_add_f32_e32 v83, 1.0, v83
	v_rcp_f32_e32 v84, v83
	v_mul_f32_e32 v83, 0xbfb8aa3b, v79
	v_exp_f32_e32 v83, v83
	s_nop 0
	v_add_f32_e32 v83, 1.0, v83
	v_rcp_f32_e32 v85, v83
	v_pk_mul_f32 v[74:75], v[74:75], v[82:83] op_sel_hi:[1,0]
	v_pk_mul_f32 v[76:77], v[76:77], v[82:83] op_sel_hi:[1,0]
	v_pk_mul_f32 v[70:71], v[70:71], v[82:83] op_sel_hi:[1,0]
	v_pk_mul_f32 v[78:79], v[78:79], v[84:85]
	v_pk_mul_f32 v[66:67], v[66:67], v[82:83] op_sel_hi:[1,0]
	v_pk_mul_f32 v[74:75], v[74:75], v[78:79]
	v_pk_mul_f32 v[78:79], v[80:81], v[82:83] op_sel_hi:[1,0]
	v_cvt_pk_bf16_f32 v74, v74, v75
	v_mul_f32_e32 v80, 0xbfb8aa3b, v78
	v_mul_f32_e32 v81, 0xbfb8aa3b, v79
	v_exp_f32_e32 v80, v80
	v_exp_f32_e32 v81, v81
	v_pk_mul_f32 v[68:69], v[68:69], v[82:83] op_sel_hi:[1,0]
	v_add_f32_e32 v80, 1.0, v80
	v_add_f32_e32 v81, 1.0, v81
	v_rcp_f32_e32 v80, v80
	v_rcp_f32_e32 v81, v81
	s_nop 0
	v_pk_mul_f32 v[78:79], v[78:79], v[80:81]
	s_nop 0
	v_pk_mul_f32 v[76:77], v[76:77], v[78:79]
	s_nop 0
	v_cvt_pk_bf16_f32 v75, v76, v77
	v_mad_i64_i32 v[76:77], s[20:21], v90, s1, v[122:123]
	v_lshl_add_u64 v[76:77], v[76:77], 0, v[124:125]
	v_mov_b32_e32 v238, v74
	v_mov_b32_e32 v239, v75
	s_nop 1
	v_permlane16_swap_b32_e32 v236, v238
	v_permlane16_swap_b32_e32 v237, v239
	global_store_dwordx4 v[244:245], v[236:239], off
	v_mul_f32_e32 v74, 0xbfb8aa3b, v70
	v_mul_f32_e32 v75, 0xbfb8aa3b, v71
	v_exp_f32_e32 v74, v74
	v_exp_f32_e32 v75, v75
	v_add_f32_e32 v74, 1.0, v74
	v_add_f32_e32 v75, 1.0, v75
	v_rcp_f32_e32 v74, v74
	v_rcp_f32_e32 v75, v75
	s_nop 0
	v_pk_mul_f32 v[70:71], v[70:71], v[74:75]
	s_nop 0
	v_pk_mul_f32 v[66:67], v[66:67], v[70:71]
	v_pk_mul_f32 v[70:71], v[72:73], v[82:83] op_sel_hi:[1,0]
	v_add_u32_e32 v74, 0x80, v140
	v_mul_f32_e32 v72, 0xbfb8aa3b, v70
	v_mul_f32_e32 v73, 0xbfb8aa3b, v71
	v_exp_f32_e32 v72, v72
	v_exp_f32_e32 v73, v73
	v_cvt_pk_bf16_f32 v66, v66, v67
	v_ashrrev_i32_e32 v75, 31, v74
	v_add_f32_e32 v72, 1.0, v72
	v_add_f32_e32 v73, 1.0, v73
	v_rcp_f32_e32 v72, v72
	v_rcp_f32_e32 v73, v73
	s_nop 0
	v_pk_mul_f32 v[70:71], v[70:71], v[72:73]
	s_nop 0
	v_pk_mul_f32 v[68:69], v[68:69], v[70:71]
	s_nop 0
	v_cvt_pk_bf16_f32 v67, v68, v69
	v_mov_b32_e32 v242, v66
	v_mov_b32_e32 v243, v67
	s_nop 1
	v_permlane16_swap_b32_e32 v240, v242
	v_permlane16_swap_b32_e32 v241, v243
	global_store_dwordx4 v[244:245], v[240:243], off offset:128
	v_mov_b32_e32 v66, v208
	v_pk_mul_f32 v[62:63], v[62:63], v[66:67] op_sel_hi:[1,0]
	s_nop 0
	v_mul_f32_e32 v67, 0xbfb8aa3b, v62
	v_exp_f32_e32 v67, v67
	s_nop 0
	v_add_f32_e32 v67, 1.0, v67
	v_rcp_f32_e32 v68, v67
	v_mul_f32_e32 v67, 0xbfb8aa3b, v63
	v_exp_f32_e32 v67, v67
	s_nop 0
	v_add_f32_e32 v67, 1.0, v67
	v_rcp_f32_e32 v69, v67
	v_pk_mul_f32 v[58:59], v[58:59], v[66:67] op_sel_hi:[1,0]
	v_pk_mul_f32 v[60:61], v[60:61], v[66:67] op_sel_hi:[1,0]
	v_pk_mul_f32 v[54:55], v[54:55], v[66:67] op_sel_hi:[1,0]
	v_pk_mul_f32 v[62:63], v[62:63], v[68:69]
	v_pk_mul_f32 v[50:51], v[50:51], v[66:67] op_sel_hi:[1,0]
	v_pk_mul_f32 v[58:59], v[58:59], v[62:63]
	v_pk_mul_f32 v[62:63], v[64:65], v[66:67] op_sel_hi:[1,0]
	v_cvt_pk_bf16_f32 v58, v58, v59
	v_mul_f32_e32 v64, 0xbfb8aa3b, v62
	v_mul_f32_e32 v65, 0xbfb8aa3b, v63
	v_exp_f32_e32 v64, v64
	v_exp_f32_e32 v65, v65
	v_pk_mul_f32 v[52:53], v[52:53], v[66:67] op_sel_hi:[1,0]
	v_add_f32_e32 v64, 1.0, v64
	v_add_f32_e32 v65, 1.0, v65
	v_rcp_f32_e32 v64, v64
	v_rcp_f32_e32 v65, v65
	s_nop 0
	v_pk_mul_f32 v[62:63], v[62:63], v[64:65]
	s_nop 0
	v_pk_mul_f32 v[60:61], v[60:61], v[62:63]
	s_nop 0
	v_cvt_pk_bf16_f32 v59, v60, v61
	v_mad_i64_i32 v[60:61], s[20:21], v74, s1, v[122:123]
	v_lshl_add_u64 v[60:61], v[60:61], 0, v[124:125]
	v_lshl_add_u64 v[244:245], v[60:61], 0, v[246:247]
	v_mov_b32_e32 v236, v58
	v_mov_b32_e32 v237, v59
	v_mul_f32_e32 v58, 0xbfb8aa3b, v54
	v_mul_f32_e32 v59, 0xbfb8aa3b, v55
	v_exp_f32_e32 v58, v58
	v_exp_f32_e32 v59, v59
	v_add_f32_e32 v58, 1.0, v58
	v_add_f32_e32 v59, 1.0, v59
	v_rcp_f32_e32 v58, v58
	v_rcp_f32_e32 v59, v59
	s_nop 0
	v_pk_mul_f32 v[54:55], v[54:55], v[58:59]
	s_nop 0
	v_pk_mul_f32 v[50:51], v[50:51], v[54:55]
	v_pk_mul_f32 v[54:55], v[56:57], v[66:67] op_sel_hi:[1,0]
	v_add_u32_e32 v58, 0x90, v140
	v_mul_f32_e32 v56, 0xbfb8aa3b, v54
	v_mul_f32_e32 v57, 0xbfb8aa3b, v55
	v_exp_f32_e32 v56, v56
	v_exp_f32_e32 v57, v57
	v_cvt_pk_bf16_f32 v50, v50, v51
	v_ashrrev_i32_e32 v59, 31, v58
	v_add_f32_e32 v56, 1.0, v56
	v_add_f32_e32 v57, 1.0, v57
	v_rcp_f32_e32 v56, v56
	v_rcp_f32_e32 v57, v57
	s_nop 0
	v_pk_mul_f32 v[54:55], v[54:55], v[56:57]
	s_nop 0
	v_pk_mul_f32 v[52:53], v[52:53], v[54:55]
	s_nop 0
	v_cvt_pk_bf16_f32 v51, v52, v53
	v_mov_b32_e32 v240, v50
	v_mov_b32_e32 v241, v51
	v_mov_b32_e32 v50, v209
	v_pk_mul_f32 v[46:47], v[46:47], v[50:51] op_sel_hi:[1,0]
	s_nop 0
	v_mul_f32_e32 v51, 0xbfb8aa3b, v46
	v_exp_f32_e32 v51, v51
	s_nop 0
	v_add_f32_e32 v51, 1.0, v51
	v_rcp_f32_e32 v52, v51
	v_mul_f32_e32 v51, 0xbfb8aa3b, v47
	v_exp_f32_e32 v51, v51
	s_nop 0
	v_add_f32_e32 v51, 1.0, v51
	v_rcp_f32_e32 v53, v51
	v_pk_mul_f32 v[42:43], v[42:43], v[50:51] op_sel_hi:[1,0]
	v_pk_mul_f32 v[44:45], v[44:45], v[50:51] op_sel_hi:[1,0]
	v_pk_mul_f32 v[38:39], v[38:39], v[50:51] op_sel_hi:[1,0]
	v_pk_mul_f32 v[46:47], v[46:47], v[52:53]
	v_pk_mul_f32 v[34:35], v[34:35], v[50:51] op_sel_hi:[1,0]
	v_pk_mul_f32 v[42:43], v[42:43], v[46:47]
	v_pk_mul_f32 v[46:47], v[48:49], v[50:51] op_sel_hi:[1,0]
	v_cvt_pk_bf16_f32 v42, v42, v43
	v_mul_f32_e32 v48, 0xbfb8aa3b, v46
	v_mul_f32_e32 v49, 0xbfb8aa3b, v47
	v_exp_f32_e32 v48, v48
	v_exp_f32_e32 v49, v49
	v_pk_mul_f32 v[36:37], v[36:37], v[50:51] op_sel_hi:[1,0]
	v_add_f32_e32 v48, 1.0, v48
	v_add_f32_e32 v49, 1.0, v49
	v_rcp_f32_e32 v48, v48
	v_rcp_f32_e32 v49, v49
	s_nop 0
	v_pk_mul_f32 v[46:47], v[46:47], v[48:49]
	s_nop 0
	v_pk_mul_f32 v[44:45], v[44:45], v[46:47]
	s_nop 0
	v_cvt_pk_bf16_f32 v43, v44, v45
	v_mad_i64_i32 v[44:45], s[20:21], v58, s1, v[122:123]
	v_lshl_add_u64 v[44:45], v[44:45], 0, v[124:125]
	v_mov_b32_e32 v238, v42
	v_mov_b32_e32 v239, v43
	s_nop 1
	v_permlane16_swap_b32_e32 v236, v238
	v_permlane16_swap_b32_e32 v237, v239
	global_store_dwordx4 v[244:245], v[236:239], off
	v_mul_f32_e32 v42, 0xbfb8aa3b, v38
	v_mul_f32_e32 v43, 0xbfb8aa3b, v39
	v_exp_f32_e32 v42, v42
	v_exp_f32_e32 v43, v43
	v_add_f32_e32 v42, 1.0, v42
	v_add_f32_e32 v43, 1.0, v43
	v_rcp_f32_e32 v42, v42
	v_rcp_f32_e32 v43, v43
	s_nop 0
	v_pk_mul_f32 v[38:39], v[38:39], v[42:43]
	s_nop 0
	v_pk_mul_f32 v[34:35], v[34:35], v[38:39]
	v_pk_mul_f32 v[38:39], v[40:41], v[50:51] op_sel_hi:[1,0]
	v_add_u32_e32 v42, 0xa0, v140
	v_mul_f32_e32 v40, 0xbfb8aa3b, v38
	v_mul_f32_e32 v41, 0xbfb8aa3b, v39
	v_exp_f32_e32 v40, v40
	v_exp_f32_e32 v41, v41
	v_cvt_pk_bf16_f32 v34, v34, v35
	v_ashrrev_i32_e32 v43, 31, v42
	v_add_f32_e32 v40, 1.0, v40
	v_add_f32_e32 v41, 1.0, v41
	v_rcp_f32_e32 v40, v40
	v_rcp_f32_e32 v41, v41
	s_nop 0
	v_pk_mul_f32 v[38:39], v[38:39], v[40:41]
	s_nop 0
	v_pk_mul_f32 v[36:37], v[36:37], v[38:39]
	s_nop 0
	v_cvt_pk_bf16_f32 v35, v36, v37
	v_mov_b32_e32 v242, v34
	v_mov_b32_e32 v243, v35
	s_nop 1
	v_permlane16_swap_b32_e32 v240, v242
	v_permlane16_swap_b32_e32 v241, v243
	global_store_dwordx4 v[244:245], v[240:243], off offset:128
	v_mov_b32_e32 v34, v210
	v_pk_mul_f32 v[30:31], v[30:31], v[34:35] op_sel_hi:[1,0]
	s_nop 0
	v_mul_f32_e32 v35, 0xbfb8aa3b, v30
	v_exp_f32_e32 v35, v35
	s_nop 0
	v_add_f32_e32 v35, 1.0, v35
	v_rcp_f32_e32 v36, v35
	v_mul_f32_e32 v35, 0xbfb8aa3b, v31
	v_exp_f32_e32 v35, v35
	s_nop 0
	v_add_f32_e32 v35, 1.0, v35
	v_rcp_f32_e32 v37, v35
	v_pk_mul_f32 v[26:27], v[26:27], v[34:35] op_sel_hi:[1,0]
	v_pk_mul_f32 v[28:29], v[28:29], v[34:35] op_sel_hi:[1,0]
	v_pk_mul_f32 v[22:23], v[22:23], v[34:35] op_sel_hi:[1,0]
	v_pk_mul_f32 v[30:31], v[30:31], v[36:37]
	v_pk_mul_f32 v[18:19], v[18:19], v[34:35] op_sel_hi:[1,0]
	v_pk_mul_f32 v[26:27], v[26:27], v[30:31]
	v_pk_mul_f32 v[30:31], v[32:33], v[34:35] op_sel_hi:[1,0]
	v_cvt_pk_bf16_f32 v26, v26, v27
	v_mul_f32_e32 v32, 0xbfb8aa3b, v30
	v_mul_f32_e32 v33, 0xbfb8aa3b, v31
	v_exp_f32_e32 v32, v32
	v_exp_f32_e32 v33, v33
	v_pk_mul_f32 v[20:21], v[20:21], v[34:35] op_sel_hi:[1,0]
	v_add_f32_e32 v32, 1.0, v32
	v_add_f32_e32 v33, 1.0, v33
	v_rcp_f32_e32 v32, v32
	v_rcp_f32_e32 v33, v33
	s_nop 0
	v_pk_mul_f32 v[30:31], v[30:31], v[32:33]
	s_nop 0
	v_pk_mul_f32 v[28:29], v[28:29], v[30:31]
	s_nop 0
	v_cvt_pk_bf16_f32 v27, v28, v29
	v_mad_i64_i32 v[28:29], s[20:21], v42, s1, v[122:123]
	v_lshl_add_u64 v[28:29], v[28:29], 0, v[124:125]
	v_lshl_add_u64 v[244:245], v[28:29], 0, v[246:247]
	v_mov_b32_e32 v236, v26
	v_mov_b32_e32 v237, v27
	v_mul_f32_e32 v26, 0xbfb8aa3b, v22
	v_mul_f32_e32 v27, 0xbfb8aa3b, v23
	v_exp_f32_e32 v26, v26
	v_exp_f32_e32 v27, v27
	v_add_f32_e32 v26, 1.0, v26
	v_add_f32_e32 v27, 1.0, v27
	v_rcp_f32_e32 v26, v26
	v_rcp_f32_e32 v27, v27
	s_nop 0
	v_pk_mul_f32 v[22:23], v[22:23], v[26:27]
	s_nop 0
	v_pk_mul_f32 v[18:19], v[18:19], v[22:23]
	v_pk_mul_f32 v[22:23], v[24:25], v[34:35] op_sel_hi:[1,0]
	v_add_u32_e32 v26, 0xb0, v140
	v_mul_f32_e32 v24, 0xbfb8aa3b, v22
	v_mul_f32_e32 v25, 0xbfb8aa3b, v23
	v_exp_f32_e32 v24, v24
	v_exp_f32_e32 v25, v25
	v_cvt_pk_bf16_f32 v18, v18, v19
	v_ashrrev_i32_e32 v27, 31, v26
	v_add_f32_e32 v24, 1.0, v24
	v_add_f32_e32 v25, 1.0, v25
	v_rcp_f32_e32 v24, v24
	v_rcp_f32_e32 v25, v25
	s_nop 0
	v_pk_mul_f32 v[22:23], v[22:23], v[24:25]
	s_nop 0
	v_pk_mul_f32 v[20:21], v[20:21], v[22:23]
	s_nop 0
	v_cvt_pk_bf16_f32 v19, v20, v21
	v_mov_b32_e32 v240, v18
	v_mov_b32_e32 v241, v19
	v_mov_b32_e32 v18, v211
	v_pk_mul_f32 v[14:15], v[14:15], v[18:19] op_sel_hi:[1,0]
	s_andn2_b64 vcc, exec, s[4:5]
	v_mul_f32_e32 v19, 0xbfb8aa3b, v14
	v_exp_f32_e32 v19, v19
	s_nop 0
	v_add_f32_e32 v19, 1.0, v19
	v_rcp_f32_e32 v20, v19
	v_mul_f32_e32 v19, 0xbfb8aa3b, v15
	v_exp_f32_e32 v19, v19
	s_nop 0
	v_add_f32_e32 v19, 1.0, v19
	v_rcp_f32_e32 v21, v19
	v_pk_mul_f32 v[10:11], v[10:11], v[18:19] op_sel_hi:[1,0]
	v_pk_mul_f32 v[12:13], v[12:13], v[18:19] op_sel_hi:[1,0]
	v_pk_mul_f32 v[6:7], v[6:7], v[18:19] op_sel_hi:[1,0]
	v_pk_mul_f32 v[14:15], v[14:15], v[20:21]
	v_pk_mul_f32 v[2:3], v[2:3], v[18:19] op_sel_hi:[1,0]
	v_pk_mul_f32 v[10:11], v[10:11], v[14:15]
	v_pk_mul_f32 v[14:15], v[16:17], v[18:19] op_sel_hi:[1,0]
	v_cvt_pk_bf16_f32 v10, v10, v11
	v_mul_f32_e32 v16, 0xbfb8aa3b, v14
	v_mul_f32_e32 v17, 0xbfb8aa3b, v15
	v_exp_f32_e32 v16, v16
	v_exp_f32_e32 v17, v17
	v_pk_mul_f32 v[4:5], v[4:5], v[18:19] op_sel_hi:[1,0]
	v_add_f32_e32 v16, 1.0, v16
	v_add_f32_e32 v17, 1.0, v17
	v_rcp_f32_e32 v16, v16
	v_rcp_f32_e32 v17, v17
	s_nop 0
	v_pk_mul_f32 v[14:15], v[14:15], v[16:17]
	s_nop 0
	v_pk_mul_f32 v[12:13], v[12:13], v[14:15]
	s_nop 0
	v_cvt_pk_bf16_f32 v11, v12, v13
	v_mad_i64_i32 v[12:13], s[20:21], v26, s1, v[122:123]
	v_lshl_add_u64 v[12:13], v[12:13], 0, v[124:125]
	v_mov_b32_e32 v238, v10
	v_mov_b32_e32 v239, v11
	s_nop 1
	v_permlane16_swap_b32_e32 v236, v238
	v_permlane16_swap_b32_e32 v237, v239
	global_store_dwordx4 v[244:245], v[236:239], off
	v_mul_f32_e32 v10, 0xbfb8aa3b, v6
	v_mul_f32_e32 v11, 0xbfb8aa3b, v7
	v_exp_f32_e32 v10, v10
	v_exp_f32_e32 v11, v11
	s_mov_b64 s[20:21], -1
	v_add_f32_e32 v10, 1.0, v10
	v_add_f32_e32 v11, 1.0, v11
	v_rcp_f32_e32 v10, v10
	v_rcp_f32_e32 v11, v11
	s_nop 0
	v_pk_mul_f32 v[6:7], v[6:7], v[10:11]
	s_nop 0
	v_pk_mul_f32 v[2:3], v[2:3], v[6:7]
	v_pk_mul_f32 v[6:7], v[8:9], v[18:19] op_sel_hi:[1,0]
	v_cvt_pk_bf16_f32 v2, v2, v3
	v_mul_f32_e32 v8, 0xbfb8aa3b, v6
	v_mul_f32_e32 v9, 0xbfb8aa3b, v7
	v_exp_f32_e32 v8, v8
	v_exp_f32_e32 v9, v9
	v_add_f32_e32 v8, 1.0, v8
	v_add_f32_e32 v9, 1.0, v9
	v_rcp_f32_e32 v8, v8
	v_rcp_f32_e32 v9, v9
	s_nop 0
	v_pk_mul_f32 v[6:7], v[6:7], v[8:9]
	s_nop 0
	v_pk_mul_f32 v[4:5], v[4:5], v[6:7]
	s_nop 0
	v_cvt_pk_bf16_f32 v3, v4, v5
	v_mov_b32_e32 v242, v2
	v_mov_b32_e32 v243, v3
	s_nop 1
	v_permlane16_swap_b32_e32 v240, v242
	v_permlane16_swap_b32_e32 v241, v243
	global_store_dwordx4 v[244:245], v[240:243], off offset:128
	s_cbranch_vccnz .LBB0_230
	s_andn2_b64 vcc, exec, s[6:7]
	s_cbranch_vccnz .LBB0_229
	s_barrier
	s_branch .LBB0_229

.LBB0_388:
	v_lshrrev_b32_e32 v18, 1, v16
	s_add_u32 s6, s66, 0xea78400
	v_and_b32_e32 v18, 24, v18
	s_addc_u32 s7, s67, 0
	v_and_b32_e32 v17, 15, v16
	v_lshlrev_b32_e32 v19, 1, v18
	v_lshlrev_b32_e32 v16, 2, v16
	s_lshl_b32 s9, s9, 5
	v_lshl_or_b32 v144, s12, 6, v17
	v_lshl_or_b32 v17, v17, 6, v19
	s_lshl_b32 s12, s12, 13
	v_and_b32_e32 v16, 32, v16
	s_and_b32 s9, s9, 0x60
	s_add_i32 m0, s31, 0x18000
	v_lshl_add_u64 v[8:9], v[8:9], 0, s[80:81]
	v_bitop3_b32 v19, v17, s12, v16 bitop3:0xde
	s_lshl_b32 s12, s9, 7
	s_waitcnt vmcnt(2)
	s_barrier
	global_load_lds_dwordx4 v[8:9], off
	v_lshl_add_u64 v[6:7], v[6:7], 0, s[80:81]
	s_add_i32 m0, s31, 0x1a000
	s_add_i32 s37, s31, 0x8000
	s_add_i32 s38, s31, 0xa000
	v_bitop3_b32 v145, v17, s12, v16 bitop3:0xde
	global_load_lds_dwordx4 v[6:7], off
	v_lshl_add_u64 v[2:3], v[2:3], 0, s[80:81]
	s_mov_b32 m0, s37
	s_add_u32 s12, s22, 0x40080
	global_load_lds_dwordx4 v[2:3], off
	v_lshl_add_u64 v[2:3], v[4:5], 0, s[80:81]
	s_mov_b32 m0, s38
	s_addc_u32 s13, s23, 0
	global_load_lds_dwordx4 v[2:3], off
	s_add_i32 m0, s31, 0x1c000
	v_lshl_add_u64 v[2:3], s[12:13], 0, v[0:1]
	global_load_lds_dwordx4 v[2:3], off
	v_lshl_add_u64 v[2:3], s[12:13], 0, v[130:131]
	s_add_i32 m0, s31, 0x1e000
	s_cmpk_lt_u32 s8, 0x100
	global_load_lds_dwordx4 v[2:3], off
	v_lshlrev_b32_e32 v2, 14, v14
	v_and_b32_e32 v2, 0xffff8000, v2
	v_lshl_add_u32 v2, v13, 11, v2
	v_and_b32_e32 v3, 1, v14
	v_lshl_or_b32 v2, v3, 6, v2
	v_lshl_add_u32 v136, v15, 1, v2
	v_lshlrev_b32_e32 v2, 14, v10
	v_and_b32_e32 v2, 0xffff8000, v2
	s_waitcnt vmcnt(6)
	v_lshl_add_u32 v2, v11, 11, v2
	v_and_b32_e32 v3, 1, v10
	v_or_b32_e32 v160, s9, v18
	v_lshl_or_b32 v2, v3, 6, v2
	v_readlane_b32 s8, v250, 43
	s_cselect_b64 s[12:13], -1, 0
	v_mov_b32_e32 v137, v1
	v_lshl_add_u32 v138, v12, 1, v2
	v_mov_b32_e32 v139, v1
	s_mov_b32 s39, 0
	v_add_u32_e32 v162, 0, v19
	v_readlane_b32 s40, v250, 18
	s_mov_b32 s41, s8
	s_barrier
	v_readlane_b32 s9, v250, 44
	v_lshl_add_u32 v140, s41, 8, v144
	v_ashrrev_i32_e32 v141, 31, v140
	v_lshlrev_b64 v[164:165], 6, v[140:141]
	v_lshl_add_u64 v[164:165], s[66:67], 0, v[164:165]
	v_and_b32_e32 v166, 48, v197
	v_mov_b32_e32 v167, 0
	v_lshl_add_u64 v[164:165], v[164:165], 0, v[166:167]
	v_mov_b32_e32 v142, 0x2000
	v_mov_b32_e32 v143, 0
	v_lshl_add_u64 v[166:167], v[164:165], 0, v[142:143]
	global_load_dwordx4 v[204:207], v[164:165], off
	global_load_dwordx4 v[208:211], v[164:165], off offset:1024
	global_load_dwordx4 v[212:215], v[164:165], off offset:2048
	global_load_dwordx4 v[216:219], v[164:165], off offset:3072
	global_load_dwordx4 v[220:223], v[166:167], off
	global_load_dwordx4 v[224:227], v[166:167], off offset:1024
	global_load_dwordx4 v[228:231], v[166:167], off offset:2048
	global_load_dwordx4 v[232:235], v[166:167], off offset:3072
	v_lshlrev_b32_e32 v140, 5, v144
	v_add_u32_e32 v140, 0x20000, v140
	s_waitcnt vmcnt(0)
	v_add_f32_e32 v204, v204, v205
	v_add_f32_e32 v206, v206, v207
	v_add_f32_e32 v204, v204, v206
	v_mov_b32_e32 v205, v204
	s_nop 1
	v_permlane16_swap_b32_e32 v204, v205
	v_add_f32_e32 v204, v204, v205
	v_mov_b32_e32 v205, v204
	s_nop 1
	v_permlane32_swap_b32_e32 v204, v205
	v_add_f32_e32 v204, v204, v205
	v_fmamk_f32 v204, v204, 0x3a800000, v161
	v_cmp_gt_f32_e32 vcc, s62, v204
	v_mul_f32_e32 v205, 0x4b800000, v204
	s_nop 0
	v_cndmask_b32_e32 v204, v204, v205, vcc
	v_rsq_f32_e32 v204, v204
	s_nop 0
	v_mul_f32_e32 v205, 0x45800000, v204
	v_cndmask_b32_e32 v204, v204, v205, vcc
	v_add_f32_e32 v208, v208, v209
	v_add_f32_e32 v210, v210, v211
	v_add_f32_e32 v208, v208, v210
	v_mov_b32_e32 v209, v208
	s_nop 1
	v_permlane16_swap_b32_e32 v208, v209
	v_add_f32_e32 v208, v208, v209
	v_mov_b32_e32 v209, v208
	s_nop 1
	v_permlane32_swap_b32_e32 v208, v209
	v_add_f32_e32 v208, v208, v209
	v_fmamk_f32 v208, v208, 0x3a800000, v161
	v_cmp_gt_f32_e32 vcc, s62, v208
	v_mul_f32_e32 v209, 0x4b800000, v208
	s_nop 0
	v_cndmask_b32_e32 v208, v208, v209, vcc
	v_rsq_f32_e32 v208, v208
	s_nop 0
	v_mul_f32_e32 v209, 0x45800000, v208
	v_cndmask_b32_e32 v208, v208, v209, vcc
	v_add_f32_e32 v212, v212, v213
	v_add_f32_e32 v214, v214, v215
	v_add_f32_e32 v212, v212, v214
	v_mov_b32_e32 v213, v212
	s_nop 1
	v_permlane16_swap_b32_e32 v212, v213
	v_add_f32_e32 v212, v212, v213
	v_mov_b32_e32 v213, v212
	s_nop 1
	v_permlane32_swap_b32_e32 v212, v213
	v_add_f32_e32 v212, v212, v213
	v_fmamk_f32 v212, v212, 0x3a800000, v161
	v_cmp_gt_f32_e32 vcc, s62, v212
	v_mul_f32_e32 v213, 0x4b800000, v212
	s_nop 0
	v_cndmask_b32_e32 v212, v212, v213, vcc
	v_rsq_f32_e32 v212, v212
	s_nop 0
	v_mul_f32_e32 v213, 0x45800000, v212
	v_cndmask_b32_e32 v212, v212, v213, vcc
	v_add_f32_e32 v216, v216, v217
	v_add_f32_e32 v218, v218, v219
	v_add_f32_e32 v216, v216, v218
	v_mov_b32_e32 v217, v216
	s_nop 1
	v_permlane16_swap_b32_e32 v216, v217
	v_add_f32_e32 v216, v216, v217
	v_mov_b32_e32 v217, v216
	s_nop 1
	v_permlane32_swap_b32_e32 v216, v217
	v_add_f32_e32 v216, v216, v217
	v_fmamk_f32 v216, v216, 0x3a800000, v161
	v_cmp_gt_f32_e32 vcc, s62, v216
	v_mul_f32_e32 v217, 0x4b800000, v216
	s_nop 0
	v_cndmask_b32_e32 v216, v216, v217, vcc
	v_rsq_f32_e32 v216, v216
	s_nop 0
	v_mul_f32_e32 v217, 0x45800000, v216
	v_cndmask_b32_e32 v216, v216, v217, vcc
	v_add_f32_e32 v220, v220, v221
	v_add_f32_e32 v222, v222, v223
	v_add_f32_e32 v220, v220, v222
	v_mov_b32_e32 v221, v220
	s_nop 1
	v_permlane16_swap_b32_e32 v220, v221
	v_add_f32_e32 v220, v220, v221
	v_mov_b32_e32 v221, v220
	s_nop 1
	v_permlane32_swap_b32_e32 v220, v221
	v_add_f32_e32 v220, v220, v221
	v_fmamk_f32 v220, v220, 0x3a800000, v161
	v_cmp_gt_f32_e32 vcc, s62, v220
	v_mul_f32_e32 v221, 0x4b800000, v220
	s_nop 0
	v_cndmask_b32_e32 v220, v220, v221, vcc
	v_rsq_f32_e32 v220, v220
	s_nop 0
	v_mul_f32_e32 v221, 0x45800000, v220
	v_cndmask_b32_e32 v220, v220, v221, vcc
	v_add_f32_e32 v224, v224, v225
	v_add_f32_e32 v226, v226, v227
	v_add_f32_e32 v224, v224, v226
	v_mov_b32_e32 v225, v224
	s_nop 1
	v_permlane16_swap_b32_e32 v224, v225
	v_add_f32_e32 v224, v224, v225
	v_mov_b32_e32 v225, v224
	s_nop 1
	v_permlane32_swap_b32_e32 v224, v225
	v_add_f32_e32 v224, v224, v225
	v_fmamk_f32 v224, v224, 0x3a800000, v161
	v_cmp_gt_f32_e32 vcc, s62, v224
	v_mul_f32_e32 v225, 0x4b800000, v224
	s_nop 0
	v_cndmask_b32_e32 v224, v224, v225, vcc
	v_rsq_f32_e32 v224, v224
	s_nop 0
	v_mul_f32_e32 v225, 0x45800000, v224
	v_cndmask_b32_e32 v224, v224, v225, vcc
	v_add_f32_e32 v228, v228, v229
	v_add_f32_e32 v230, v230, v231
	v_add_f32_e32 v228, v228, v230
	v_mov_b32_e32 v229, v228
	s_nop 1
	v_permlane16_swap_b32_e32 v228, v229
	v_add_f32_e32 v228, v228, v229
	v_mov_b32_e32 v229, v228
	s_nop 1
	v_permlane32_swap_b32_e32 v228, v229
	v_add_f32_e32 v228, v228, v229
	v_fmamk_f32 v228, v228, 0x3a800000, v161
	v_cmp_gt_f32_e32 vcc, s62, v228
	v_mul_f32_e32 v229, 0x4b800000, v228
	s_nop 0
	v_cndmask_b32_e32 v228, v228, v229, vcc
	v_rsq_f32_e32 v228, v228
	s_nop 0
	v_mul_f32_e32 v229, 0x45800000, v228
	v_cndmask_b32_e32 v228, v228, v229, vcc
	v_add_f32_e32 v232, v232, v233
	v_add_f32_e32 v234, v234, v235
	v_add_f32_e32 v232, v232, v234
	v_mov_b32_e32 v233, v232
	s_nop 1
	v_permlane16_swap_b32_e32 v232, v233
	v_add_f32_e32 v232, v232, v233
	v_mov_b32_e32 v233, v232
	s_nop 1
	v_permlane32_swap_b32_e32 v232, v233
	v_add_f32_e32 v232, v232, v233
	v_fmamk_f32 v232, v232, 0x3a800000, v161
	v_cmp_gt_f32_e32 vcc, s62, v232
	v_mul_f32_e32 v233, 0x4b800000, v232
	s_nop 0
	v_cndmask_b32_e32 v232, v232, v233, vcc
	v_rsq_f32_e32 v232, v232
	s_nop 0
	v_mul_f32_e32 v233, 0x45800000, v232
	v_cndmask_b32_e32 v232, v232, v233, vcc
	ds_write_b32 v140, v204
	ds_write_b32 v140, v208 offset:4
	ds_write_b32 v140, v212 offset:8
	ds_write_b32 v140, v216 offset:12
	ds_write_b32 v140, v220 offset:16
	ds_write_b32 v140, v224 offset:20
	ds_write_b32 v140, v228 offset:24
	ds_write_b32 v140, v232 offset:28
	s_waitcnt lgkmcnt(0)
	s_branch .LBB0_391

.LBB0_397:
	v_lshl_add_u32 v140, s41, 8, v144
	v_ashrrev_i32_e32 v141, 31, v140
	v_lshlrev_b64 v[164:165], 6, v[140:141]
	v_lshl_add_u64 v[164:165], s[66:67], 0, v[164:165]
	v_and_b32_e32 v166, 48, v197
	v_mov_b32_e32 v167, 0
	v_lshl_add_u64 v[164:165], v[164:165], 0, v[166:167]
	s_mov_b64 s[10:11], 0x2000
	v_lshl_add_u64 v[166:167], v[164:165], 0, s[10:11]
	s_add_i32 s15, s40, -6
	s_sub_i32 s10, s40, 18
	s_cmp_lt_u32 s10, 12
	s_cselect_b32 s17, 3, 0
	s_cmp_lt_u32 s15, 6
	s_cselect_b64 s[10:11], -1, 0
	s_and_b64 s[22:23], s[10:11], exec
	s_cselect_b32 s17, 2, s17
	s_cmp_lt_u32 s15, -3
	s_cselect_b32 s15, s17, 1
	s_cmp_gt_i32 s15, 2
	s_mov_b64 s[22:23], -1
	v_lshlrev_b32_e32 v212, 5, v144
	v_add_u32_e32 v212, 0x20000, v212
	ds_read_b128 v[204:207], v212
	ds_read_b128 v[208:211], v212 offset:16
	s_waitcnt lgkmcnt(0)
	v_mov_b32_e32 v141, v204
	v_mul_f32_e32 v142, 0x3e38aa3b, v141
	v_cndmask_b32_e64 v142, v141, v142, s[10:11]
	v_pk_mul_f32 v[128:129], v[128:129], v[142:143] op_sel_hi:[1,0]
	v_pk_mul_f32 v[126:127], v[126:127], v[142:143] op_sel_hi:[1,0]
	v_pk_mul_f32 v[124:125], v[124:125], v[142:143] op_sel_hi:[1,0]
	v_pk_mul_f32 v[122:123], v[122:123], v[142:143] op_sel_hi:[1,0]
	s_cbranch_scc0 .LBB0_399
	v_mul_f32_e32 v143, 0xbfb8aa3b, v122
	v_exp_f32_e32 v143, v143
	v_mul_f32_e32 v163, 0xbfb8aa3b, v127
	v_exp_f32_e32 v164, v163
	v_mul_f32_e32 v163, 0xbfb8aa3b, v123
	v_exp_f32_e32 v165, v163
	v_add_f32_e32 v143, 1.0, v143
	v_rcp_f32_e32 v163, v143
	v_add_f32_e32 v143, 1.0, v164
	v_rcp_f32_e32 v164, v143
	v_add_f32_e32 v143, 1.0, v165
	v_mul_f32_e32 v165, 0xbfb8aa3b, v128
	v_exp_f32_e32 v166, v165
	v_mul_f32_e32 v165, 0xbfb8aa3b, v124
	v_exp_f32_e32 v167, v165
	v_rcp_f32_e32 v165, v143
	v_add_f32_e32 v143, 1.0, v166
	v_rcp_f32_e32 v166, v143
	v_add_f32_e32 v143, 1.0, v167
	v_mul_f32_e32 v167, 0xbfb8aa3b, v129
	v_mul_f32_e32 v141, 0xbfb8aa3b, v126
	v_exp_f32_e32 v168, v167
	v_mul_f32_e32 v167, 0xbfb8aa3b, v125
	v_exp_f32_e32 v141, v141
	v_exp_f32_e32 v170, v167
	v_rcp_f32_e32 v167, v143
	v_add_f32_e32 v143, 1.0, v168
	v_add_f32_e32 v141, 1.0, v141
	v_rcp_f32_e32 v169, v143
	v_add_f32_e32 v143, 1.0, v170
	v_rcp_f32_e32 v141, v141
	v_rcp_f32_e32 v168, v143
	s_mov_b64 s[22:23], 0

.LBB0_409:
	v_cvt_pk_bf16_f32 v114, v126, v128
	v_cvt_pk_bf16_f32 v115, v141, v163
	v_cvt_pk_bf16_f32 v116, v127, v129
	v_cvt_pk_bf16_f32 v117, v142, v143
	global_store_dwordx4 v[124:125], v[114:117], off offset:256
	s_cmp_gt_i32 s15, 2
	s_mov_b64 s[22:23], -1
	v_or_b32_e32 v114, 16, v140
	v_ashrrev_i32_e32 v115, 31, v114
	v_mov_b32_e32 v115, v205
	v_mul_f32_e32 v116, 0x3e38aa3b, v115
	v_cndmask_b32_e64 v116, v115, v116, s[10:11]
	v_pk_mul_f32 v[112:113], v[112:113], v[116:117] op_sel_hi:[1,0]
	v_pk_mul_f32 v[110:111], v[110:111], v[116:117] op_sel_hi:[1,0]
	v_pk_mul_f32 v[108:109], v[108:109], v[116:117] op_sel_hi:[1,0]
	v_pk_mul_f32 v[106:107], v[106:107], v[116:117] op_sel_hi:[1,0]
	s_cbranch_scc0 .LBB0_411
	v_mul_f32_e32 v117, 0xbfb8aa3b, v106
	v_exp_f32_e32 v117, v117
	v_mul_f32_e32 v118, 0xbfb8aa3b, v111
	v_exp_f32_e32 v119, v118
	v_mul_f32_e32 v118, 0xbfb8aa3b, v107
	v_exp_f32_e32 v120, v118
	v_add_f32_e32 v117, 1.0, v117
	v_rcp_f32_e32 v118, v117
	v_add_f32_e32 v117, 1.0, v119
	v_rcp_f32_e32 v119, v117
	v_add_f32_e32 v117, 1.0, v120
	v_mul_f32_e32 v120, 0xbfb8aa3b, v112
	v_exp_f32_e32 v121, v120
	v_mul_f32_e32 v120, 0xbfb8aa3b, v108
	v_exp_f32_e32 v124, v120
	v_rcp_f32_e32 v120, v117
	v_add_f32_e32 v117, 1.0, v121
	v_rcp_f32_e32 v121, v117
	v_add_f32_e32 v117, 1.0, v124
	v_mul_f32_e32 v124, 0xbfb8aa3b, v113
	v_mul_f32_e32 v115, 0xbfb8aa3b, v110
	v_exp_f32_e32 v125, v124
	v_mul_f32_e32 v124, 0xbfb8aa3b, v109
	v_exp_f32_e32 v115, v115
	v_exp_f32_e32 v127, v124
	v_rcp_f32_e32 v124, v117
	v_add_f32_e32 v117, 1.0, v125
	v_add_f32_e32 v115, 1.0, v115
	v_rcp_f32_e32 v126, v117
	v_add_f32_e32 v117, 1.0, v127
	v_rcp_f32_e32 v115, v115
	v_rcp_f32_e32 v125, v117
	s_mov_b64 s[22:23], 0

.LBB0_421:
	v_cvt_pk_bf16_f32 v98, v108, v110
	v_cvt_pk_bf16_f32 v99, v112, v115
	v_cvt_pk_bf16_f32 v100, v109, v111
	v_cvt_pk_bf16_f32 v101, v113, v114
	global_store_dwordx4 v[106:107], v[98:101], off offset:256
	s_cmp_gt_i32 s15, 2
	s_mov_b64 s[22:23], -1
	v_or_b32_e32 v98, 32, v140
	v_ashrrev_i32_e32 v99, 31, v98
	v_mov_b32_e32 v99, v206
	v_mul_f32_e32 v100, 0x3e38aa3b, v99
	v_cndmask_b32_e64 v100, v99, v100, s[10:11]
	v_pk_mul_f32 v[96:97], v[96:97], v[100:101] op_sel_hi:[1,0]
	v_pk_mul_f32 v[94:95], v[94:95], v[100:101] op_sel_hi:[1,0]
	v_pk_mul_f32 v[92:93], v[92:93], v[100:101] op_sel_hi:[1,0]
	v_pk_mul_f32 v[90:91], v[90:91], v[100:101] op_sel_hi:[1,0]
	s_cbranch_scc0 .LBB0_423
	v_mul_f32_e32 v101, 0xbfb8aa3b, v90
	v_exp_f32_e32 v101, v101
	v_mul_f32_e32 v102, 0xbfb8aa3b, v95
	v_exp_f32_e32 v103, v102
	v_mul_f32_e32 v102, 0xbfb8aa3b, v91
	v_exp_f32_e32 v104, v102
	v_add_f32_e32 v101, 1.0, v101
	v_rcp_f32_e32 v102, v101
	v_add_f32_e32 v101, 1.0, v103
	v_rcp_f32_e32 v103, v101
	v_add_f32_e32 v101, 1.0, v104
	v_mul_f32_e32 v104, 0xbfb8aa3b, v96
	v_exp_f32_e32 v105, v104
	v_mul_f32_e32 v104, 0xbfb8aa3b, v92
	v_exp_f32_e32 v106, v104
	v_rcp_f32_e32 v104, v101
	v_add_f32_e32 v101, 1.0, v105
	v_rcp_f32_e32 v105, v101
	v_add_f32_e32 v101, 1.0, v106
	v_mul_f32_e32 v106, 0xbfb8aa3b, v97
	v_mul_f32_e32 v99, 0xbfb8aa3b, v94
	v_exp_f32_e32 v107, v106
	v_mul_f32_e32 v106, 0xbfb8aa3b, v93
	v_exp_f32_e32 v99, v99
	v_exp_f32_e32 v109, v106
	v_rcp_f32_e32 v106, v101
	v_add_f32_e32 v101, 1.0, v107
	v_add_f32_e32 v99, 1.0, v99
	v_rcp_f32_e32 v108, v101
	v_add_f32_e32 v101, 1.0, v109
	v_rcp_f32_e32 v99, v99
	v_rcp_f32_e32 v107, v101
	s_mov_b64 s[22:23], 0

.LBB0_433:
	v_cvt_pk_bf16_f32 v82, v92, v94
	v_cvt_pk_bf16_f32 v83, v96, v99
	v_cvt_pk_bf16_f32 v84, v93, v95
	v_cvt_pk_bf16_f32 v85, v97, v98
	global_store_dwordx4 v[90:91], v[82:85], off offset:256
	s_cmp_gt_i32 s15, 2
	s_mov_b64 s[22:23], -1
	v_or_b32_e32 v82, 48, v140
	v_ashrrev_i32_e32 v83, 31, v82
	v_mov_b32_e32 v83, v207
	v_mul_f32_e32 v84, 0x3e38aa3b, v83
	v_cndmask_b32_e64 v84, v83, v84, s[10:11]
	v_pk_mul_f32 v[80:81], v[80:81], v[84:85] op_sel_hi:[1,0]
	v_pk_mul_f32 v[78:79], v[78:79], v[84:85] op_sel_hi:[1,0]
	v_pk_mul_f32 v[76:77], v[76:77], v[84:85] op_sel_hi:[1,0]
	v_pk_mul_f32 v[74:75], v[74:75], v[84:85] op_sel_hi:[1,0]
	s_cbranch_scc0 .LBB0_435
	v_mul_f32_e32 v85, 0xbfb8aa3b, v74
	v_exp_f32_e32 v85, v85
	v_mul_f32_e32 v86, 0xbfb8aa3b, v79
	v_exp_f32_e32 v87, v86
	v_mul_f32_e32 v86, 0xbfb8aa3b, v75
	v_exp_f32_e32 v88, v86
	v_add_f32_e32 v85, 1.0, v85
	v_rcp_f32_e32 v86, v85
	v_add_f32_e32 v85, 1.0, v87
	v_rcp_f32_e32 v87, v85
	v_add_f32_e32 v85, 1.0, v88
	v_mul_f32_e32 v88, 0xbfb8aa3b, v80
	v_exp_f32_e32 v89, v88
	v_mul_f32_e32 v88, 0xbfb8aa3b, v76
	v_exp_f32_e32 v90, v88
	v_rcp_f32_e32 v88, v85
	v_add_f32_e32 v85, 1.0, v89
	v_rcp_f32_e32 v89, v85
	v_add_f32_e32 v85, 1.0, v90
	v_mul_f32_e32 v90, 0xbfb8aa3b, v81
	v_mul_f32_e32 v83, 0xbfb8aa3b, v78
	v_exp_f32_e32 v91, v90
	v_mul_f32_e32 v90, 0xbfb8aa3b, v77
	v_exp_f32_e32 v83, v83
	v_exp_f32_e32 v93, v90
	v_rcp_f32_e32 v90, v85
	v_add_f32_e32 v85, 1.0, v91
	v_add_f32_e32 v83, 1.0, v83
	v_rcp_f32_e32 v92, v85
	v_add_f32_e32 v85, 1.0, v93
	v_rcp_f32_e32 v83, v83
	v_rcp_f32_e32 v91, v85
	s_mov_b64 s[22:23], 0

.LBB0_445:
	v_cvt_pk_bf16_f32 v66, v76, v78
	v_cvt_pk_bf16_f32 v67, v80, v83
	v_cvt_pk_bf16_f32 v68, v77, v79
	v_cvt_pk_bf16_f32 v69, v81, v82
	global_store_dwordx4 v[74:75], v[66:69], off offset:256
	s_cmp_gt_i32 s15, 2
	s_mov_b64 s[22:23], -1
	v_add_u32_e32 v66, 0x80, v140
	v_ashrrev_i32_e32 v67, 31, v66
	v_mov_b32_e32 v67, v208
	v_mul_f32_e32 v68, 0x3e38aa3b, v67
	v_cndmask_b32_e64 v68, v67, v68, s[10:11]
	v_pk_mul_f32 v[64:65], v[64:65], v[68:69] op_sel_hi:[1,0]
	v_pk_mul_f32 v[62:63], v[62:63], v[68:69] op_sel_hi:[1,0]
	v_pk_mul_f32 v[60:61], v[60:61], v[68:69] op_sel_hi:[1,0]
	v_pk_mul_f32 v[58:59], v[58:59], v[68:69] op_sel_hi:[1,0]
	s_cbranch_scc0 .LBB0_447
	v_mul_f32_e32 v69, 0xbfb8aa3b, v58
	v_exp_f32_e32 v69, v69
	v_mul_f32_e32 v70, 0xbfb8aa3b, v63
	v_exp_f32_e32 v71, v70
	v_mul_f32_e32 v70, 0xbfb8aa3b, v59
	v_exp_f32_e32 v72, v70
	v_add_f32_e32 v69, 1.0, v69
	v_rcp_f32_e32 v70, v69
	v_add_f32_e32 v69, 1.0, v71
	v_rcp_f32_e32 v71, v69
	v_add_f32_e32 v69, 1.0, v72
	v_mul_f32_e32 v72, 0xbfb8aa3b, v64
	v_exp_f32_e32 v73, v72
	v_mul_f32_e32 v72, 0xbfb8aa3b, v60
	v_exp_f32_e32 v74, v72
	v_rcp_f32_e32 v72, v69
	v_add_f32_e32 v69, 1.0, v73
	v_rcp_f32_e32 v73, v69
	v_add_f32_e32 v69, 1.0, v74
	v_mul_f32_e32 v74, 0xbfb8aa3b, v65
	v_mul_f32_e32 v67, 0xbfb8aa3b, v62
	v_exp_f32_e32 v75, v74
	v_mul_f32_e32 v74, 0xbfb8aa3b, v61
	v_exp_f32_e32 v67, v67
	v_exp_f32_e32 v77, v74
	v_rcp_f32_e32 v74, v69
	v_add_f32_e32 v69, 1.0, v75
	v_add_f32_e32 v67, 1.0, v67
	v_rcp_f32_e32 v76, v69
	v_add_f32_e32 v69, 1.0, v77
	v_rcp_f32_e32 v67, v67
	v_rcp_f32_e32 v75, v69
	s_mov_b64 s[22:23], 0

.LBB0_457:
	v_cvt_pk_bf16_f32 v50, v60, v62
	v_cvt_pk_bf16_f32 v51, v64, v67
	v_cvt_pk_bf16_f32 v52, v61, v63
	v_cvt_pk_bf16_f32 v53, v65, v66
	global_store_dwordx4 v[58:59], v[50:53], off offset:256
	s_cmp_gt_i32 s15, 2
	s_mov_b64 s[22:23], -1
	v_add_u32_e32 v50, 0x90, v140
	v_ashrrev_i32_e32 v51, 31, v50
	v_mov_b32_e32 v51, v209
	v_mul_f32_e32 v52, 0x3e38aa3b, v51
	v_cndmask_b32_e64 v52, v51, v52, s[10:11]
	v_pk_mul_f32 v[48:49], v[48:49], v[52:53] op_sel_hi:[1,0]
	v_pk_mul_f32 v[46:47], v[46:47], v[52:53] op_sel_hi:[1,0]
	v_pk_mul_f32 v[44:45], v[44:45], v[52:53] op_sel_hi:[1,0]
	v_pk_mul_f32 v[42:43], v[42:43], v[52:53] op_sel_hi:[1,0]
	s_cbranch_scc0 .LBB0_459
	v_mul_f32_e32 v53, 0xbfb8aa3b, v42
	v_exp_f32_e32 v53, v53
	v_mul_f32_e32 v54, 0xbfb8aa3b, v47
	v_exp_f32_e32 v55, v54
	v_mul_f32_e32 v54, 0xbfb8aa3b, v43
	v_exp_f32_e32 v56, v54
	v_add_f32_e32 v53, 1.0, v53
	v_rcp_f32_e32 v54, v53
	v_add_f32_e32 v53, 1.0, v55
	v_rcp_f32_e32 v55, v53
	v_add_f32_e32 v53, 1.0, v56
	v_mul_f32_e32 v56, 0xbfb8aa3b, v48
	v_exp_f32_e32 v57, v56
	v_mul_f32_e32 v56, 0xbfb8aa3b, v44
	v_exp_f32_e32 v58, v56
	v_rcp_f32_e32 v56, v53
	v_add_f32_e32 v53, 1.0, v57
	v_rcp_f32_e32 v57, v53
	v_add_f32_e32 v53, 1.0, v58
	v_mul_f32_e32 v58, 0xbfb8aa3b, v49
	v_mul_f32_e32 v51, 0xbfb8aa3b, v46
	v_exp_f32_e32 v59, v58
	v_mul_f32_e32 v58, 0xbfb8aa3b, v45
	v_exp_f32_e32 v51, v51
	v_exp_f32_e32 v61, v58
	v_rcp_f32_e32 v58, v53
	v_add_f32_e32 v53, 1.0, v59
	v_add_f32_e32 v51, 1.0, v51
	v_rcp_f32_e32 v60, v53
	v_add_f32_e32 v53, 1.0, v61
	v_rcp_f32_e32 v51, v51
	v_rcp_f32_e32 v59, v53
	s_mov_b64 s[22:23], 0

.LBB0_469:
	v_cvt_pk_bf16_f32 v34, v44, v46
	v_cvt_pk_bf16_f32 v35, v48, v51
	v_cvt_pk_bf16_f32 v36, v45, v47
	v_cvt_pk_bf16_f32 v37, v49, v50
	global_store_dwordx4 v[42:43], v[34:37], off offset:256
	s_cmp_gt_i32 s15, 2
	s_mov_b64 s[22:23], -1
	v_add_u32_e32 v34, 0xa0, v140
	v_ashrrev_i32_e32 v35, 31, v34
	v_mov_b32_e32 v35, v210
	v_mul_f32_e32 v36, 0x3e38aa3b, v35
	v_cndmask_b32_e64 v36, v35, v36, s[10:11]
	v_pk_mul_f32 v[32:33], v[32:33], v[36:37] op_sel_hi:[1,0]
	v_pk_mul_f32 v[30:31], v[30:31], v[36:37] op_sel_hi:[1,0]
	v_pk_mul_f32 v[28:29], v[28:29], v[36:37] op_sel_hi:[1,0]
	v_pk_mul_f32 v[26:27], v[26:27], v[36:37] op_sel_hi:[1,0]
	s_cbranch_scc0 .LBB0_471
	v_mul_f32_e32 v37, 0xbfb8aa3b, v26
	v_exp_f32_e32 v37, v37
	v_mul_f32_e32 v38, 0xbfb8aa3b, v31
	v_exp_f32_e32 v39, v38
	v_mul_f32_e32 v38, 0xbfb8aa3b, v27
	v_exp_f32_e32 v40, v38
	v_add_f32_e32 v37, 1.0, v37
	v_rcp_f32_e32 v38, v37
	v_add_f32_e32 v37, 1.0, v39
	v_rcp_f32_e32 v39, v37
	v_add_f32_e32 v37, 1.0, v40
	v_mul_f32_e32 v40, 0xbfb8aa3b, v32
	v_exp_f32_e32 v41, v40
	v_mul_f32_e32 v40, 0xbfb8aa3b, v28
	v_exp_f32_e32 v42, v40
	v_rcp_f32_e32 v40, v37
	v_add_f32_e32 v37, 1.0, v41
	v_rcp_f32_e32 v41, v37
	v_add_f32_e32 v37, 1.0, v42
	v_mul_f32_e32 v42, 0xbfb8aa3b, v33
	v_mul_f32_e32 v35, 0xbfb8aa3b, v30
	v_exp_f32_e32 v43, v42
	v_mul_f32_e32 v42, 0xbfb8aa3b, v29
	v_exp_f32_e32 v35, v35
	v_exp_f32_e32 v45, v42
	v_rcp_f32_e32 v42, v37
	v_add_f32_e32 v37, 1.0, v43
	v_add_f32_e32 v35, 1.0, v35
	v_rcp_f32_e32 v44, v37
	v_add_f32_e32 v37, 1.0, v45
	v_rcp_f32_e32 v35, v35
	v_rcp_f32_e32 v43, v37
	s_mov_b64 s[22:23], 0

.LBB0_481:
	v_cvt_pk_bf16_f32 v18, v28, v30
	v_cvt_pk_bf16_f32 v19, v32, v35
	v_cvt_pk_bf16_f32 v20, v29, v31
	v_cvt_pk_bf16_f32 v21, v33, v34
	global_store_dwordx4 v[26:27], v[18:21], off offset:256
	s_cmp_gt_i32 s15, 2
	s_nop 0
	v_add_u32_e32 v18, 0xb0, v140
	v_ashrrev_i32_e32 v19, 31, v18
	v_mov_b32_e32 v19, v211
	v_mul_f32_e32 v20, 0x3e38aa3b, v19
	v_cndmask_b32_e64 v20, v19, v20, s[10:11]
	v_pk_mul_f32 v[16:17], v[16:17], v[20:21] op_sel_hi:[1,0]
	v_pk_mul_f32 v[14:15], v[14:15], v[20:21] op_sel_hi:[1,0]
	v_pk_mul_f32 v[12:13], v[12:13], v[20:21] op_sel_hi:[1,0]
	v_pk_mul_f32 v[10:11], v[10:11], v[20:21] op_sel_hi:[1,0]
	s_mov_b64 s[10:11], -1
	s_cbranch_scc0 .LBB0_483
	v_mul_f32_e32 v21, 0xbfb8aa3b, v10
	v_exp_f32_e32 v21, v21
	v_mul_f32_e32 v22, 0xbfb8aa3b, v15
	v_exp_f32_e32 v23, v22
	v_mul_f32_e32 v22, 0xbfb8aa3b, v11
	v_exp_f32_e32 v24, v22
	v_add_f32_e32 v21, 1.0, v21
	v_rcp_f32_e32 v22, v21
	v_add_f32_e32 v21, 1.0, v23
	v_rcp_f32_e32 v23, v21
	v_add_f32_e32 v21, 1.0, v24
	v_mul_f32_e32 v24, 0xbfb8aa3b, v16
	v_exp_f32_e32 v25, v24
	v_mul_f32_e32 v24, 0xbfb8aa3b, v12
	v_exp_f32_e32 v26, v24
	v_rcp_f32_e32 v24, v21
	v_add_f32_e32 v21, 1.0, v25
	v_rcp_f32_e32 v25, v21
	v_add_f32_e32 v21, 1.0, v26
	v_mul_f32_e32 v26, 0xbfb8aa3b, v17
	v_mul_f32_e32 v19, 0xbfb8aa3b, v14
	v_exp_f32_e32 v27, v26
	v_mul_f32_e32 v26, 0xbfb8aa3b, v13
	v_exp_f32_e32 v19, v19
	v_exp_f32_e32 v29, v26
	v_rcp_f32_e32 v26, v21
	v_add_f32_e32 v21, 1.0, v27
	v_add_f32_e32 v19, 1.0, v19
	v_rcp_f32_e32 v28, v21
	v_add_f32_e32 v21, 1.0, v29
	v_rcp_f32_e32 v19, v19
	v_rcp_f32_e32 v27, v21
	s_mov_b64 s[10:11], 0

.LBB0_1596:
	v_bfe_u32 v18, v16, 4, 2
	s_add_u32 s8, s66, 0xea78400
	v_and_b32_e32 v17, 15, v16
	v_lshlrev_b32_e32 v19, 4, v18
	v_lshlrev_b32_e32 v16, 2, v16
	s_addc_u32 s9, s67, 0
	s_and_b32 s12, s10, 3
	v_lshl_or_b32 v145, s7, 6, v17
	v_lshl_or_b32 v17, v17, 6, v19
	s_lshl_b32 s7, s7, 13
	v_and_b32_e32 v16, 32, v16
	s_add_i32 m0, s31, 0x18000
	v_lshl_add_u64 v[8:9], v[8:9], 0, s[80:81]
	v_bitop3_b32 v19, v17, s7, v16 bitop3:0xde
	s_lshl_b32 s7, s12, 12
	s_waitcnt vmcnt(2)
	s_barrier
	global_load_lds_dwordx4 v[8:9], off
	v_lshl_add_u64 v[6:7], v[6:7], 0, s[80:81]
	s_add_i32 m0, s31, 0x1a000
	s_add_i32 s37, s31, 0x8000
	s_add_i32 s38, s31, 0xa000
	global_load_lds_dwordx4 v[6:7], off
	v_lshl_add_u64 v[2:3], v[2:3], 0, s[80:81]
	s_mov_b32 m0, s37
	s_add_u32 s10, s22, 0x40080
	global_load_lds_dwordx4 v[2:3], off
	v_lshl_add_u64 v[2:3], v[4:5], 0, s[80:81]
	s_mov_b32 m0, s38
	s_addc_u32 s11, s23, 0
	global_load_lds_dwordx4 v[2:3], off
	s_add_i32 m0, s31, 0x1c000
	v_lshl_add_u64 v[2:3], s[10:11], 0, v[0:1]
	global_load_lds_dwordx4 v[2:3], off
	v_lshl_add_u64 v[2:3], s[10:11], 0, v[130:131]
	s_add_i32 m0, s31, 0x1e000
	v_bitop3_b32 v160, v17, s7, v16 bitop3:0xde
	global_load_lds_dwordx4 v[2:3], off
	v_lshlrev_b32_e32 v2, 2, v18
	v_lshl_or_b32 v162, s12, 4, v2
	v_lshlrev_b32_e32 v2, 14, v14
	v_and_b32_e32 v2, 0xffff8000, v2
	v_lshl_add_u32 v2, v13, 11, v2
	v_and_b32_e32 v3, 1, v14
	v_lshl_or_b32 v2, v3, 6, v2
	v_lshl_add_u32 v136, v15, 1, v2
	v_lshlrev_b32_e32 v2, 14, v10
	v_and_b32_e32 v2, 0xffff8000, v2
	s_waitcnt vmcnt(6)
	v_lshl_add_u32 v2, v11, 11, v2
	v_and_b32_e32 v3, 1, v10
	s_cmpk_lt_u32 s6, 0x100
	v_lshl_or_b32 v2, v3, 6, v2
	v_readlane_b32 s6, v250, 8
	s_cselect_b64 s[10:11], -1, 0
	v_mov_b32_e32 v137, v1
	v_lshl_add_u32 v138, v12, 1, v2
	v_mov_b32_e32 v139, v1
	s_mov_b32 s39, 0
	v_add_u32_e32 v163, 0, v19
	v_readlane_b32 s40, v250, 7
	s_mov_b32 s41, s6
	s_barrier
	v_readlane_b32 s7, v250, 9
	v_lshl_add_u32 v140, s41, 8, v145
	v_ashrrev_i32_e32 v141, 31, v140
	v_lshlrev_b64 v[164:165], 6, v[140:141]
	v_lshl_add_u64 v[164:165], s[66:67], 0, v[164:165]
	v_and_b32_e32 v166, 48, v197
	v_mov_b32_e32 v167, 0
	v_lshl_add_u64 v[164:165], v[164:165], 0, v[166:167]
	v_mov_b32_e32 v142, 0x2000
	v_mov_b32_e32 v143, 0
	v_lshl_add_u64 v[166:167], v[164:165], 0, v[142:143]
	global_load_dwordx4 v[204:207], v[164:165], off
	global_load_dwordx4 v[208:211], v[164:165], off offset:1024
	global_load_dwordx4 v[212:215], v[164:165], off offset:2048
	global_load_dwordx4 v[216:219], v[164:165], off offset:3072
	global_load_dwordx4 v[220:223], v[166:167], off
	global_load_dwordx4 v[224:227], v[166:167], off offset:1024
	global_load_dwordx4 v[228:231], v[166:167], off offset:2048
	global_load_dwordx4 v[232:235], v[166:167], off offset:3072
	v_lshlrev_b32_e32 v140, 5, v145
	v_add_u32_e32 v140, 0x20000, v140
	s_waitcnt vmcnt(0)
	v_add_f32_e32 v204, v204, v205
	v_add_f32_e32 v206, v206, v207
	v_add_f32_e32 v204, v204, v206
	v_mov_b32_e32 v205, v204
	s_nop 1
	v_permlane16_swap_b32_e32 v204, v205
	v_add_f32_e32 v204, v204, v205
	v_mov_b32_e32 v205, v204
	s_nop 1
	v_permlane32_swap_b32_e32 v204, v205
	v_add_f32_e32 v204, v204, v205
	v_fmamk_f32 v204, v204, 0x3a800000, v161
	v_cmp_gt_f32_e32 vcc, s62, v204
	v_mul_f32_e32 v205, 0x4b800000, v204
	s_nop 0
	v_cndmask_b32_e32 v204, v204, v205, vcc
	v_rsq_f32_e32 v204, v204
	s_nop 0
	v_mul_f32_e32 v205, 0x45800000, v204
	v_cndmask_b32_e32 v204, v204, v205, vcc
	v_add_f32_e32 v208, v208, v209
	v_add_f32_e32 v210, v210, v211
	v_add_f32_e32 v208, v208, v210
	v_mov_b32_e32 v209, v208
	s_nop 1
	v_permlane16_swap_b32_e32 v208, v209
	v_add_f32_e32 v208, v208, v209
	v_mov_b32_e32 v209, v208
	s_nop 1
	v_permlane32_swap_b32_e32 v208, v209
	v_add_f32_e32 v208, v208, v209
	v_fmamk_f32 v208, v208, 0x3a800000, v161
	v_cmp_gt_f32_e32 vcc, s62, v208
	v_mul_f32_e32 v209, 0x4b800000, v208
	s_nop 0
	v_cndmask_b32_e32 v208, v208, v209, vcc
	v_rsq_f32_e32 v208, v208
	s_nop 0
	v_mul_f32_e32 v209, 0x45800000, v208
	v_cndmask_b32_e32 v208, v208, v209, vcc
	v_add_f32_e32 v212, v212, v213
	v_add_f32_e32 v214, v214, v215
	v_add_f32_e32 v212, v212, v214
	v_mov_b32_e32 v213, v212
	s_nop 1
	v_permlane16_swap_b32_e32 v212, v213
	v_add_f32_e32 v212, v212, v213
	v_mov_b32_e32 v213, v212
	s_nop 1
	v_permlane32_swap_b32_e32 v212, v213
	v_add_f32_e32 v212, v212, v213
	v_fmamk_f32 v212, v212, 0x3a800000, v161
	v_cmp_gt_f32_e32 vcc, s62, v212
	v_mul_f32_e32 v213, 0x4b800000, v212
	s_nop 0
	v_cndmask_b32_e32 v212, v212, v213, vcc
	v_rsq_f32_e32 v212, v212
	s_nop 0
	v_mul_f32_e32 v213, 0x45800000, v212
	v_cndmask_b32_e32 v212, v212, v213, vcc
	v_add_f32_e32 v216, v216, v217
	v_add_f32_e32 v218, v218, v219
	v_add_f32_e32 v216, v216, v218
	v_mov_b32_e32 v217, v216
	s_nop 1
	v_permlane16_swap_b32_e32 v216, v217
	v_add_f32_e32 v216, v216, v217
	v_mov_b32_e32 v217, v216
	s_nop 1
	v_permlane32_swap_b32_e32 v216, v217
	v_add_f32_e32 v216, v216, v217
	v_fmamk_f32 v216, v216, 0x3a800000, v161
	v_cmp_gt_f32_e32 vcc, s62, v216
	v_mul_f32_e32 v217, 0x4b800000, v216
	s_nop 0
	v_cndmask_b32_e32 v216, v216, v217, vcc
	v_rsq_f32_e32 v216, v216
	s_nop 0
	v_mul_f32_e32 v217, 0x45800000, v216
	v_cndmask_b32_e32 v216, v216, v217, vcc
	v_add_f32_e32 v220, v220, v221
	v_add_f32_e32 v222, v222, v223
	v_add_f32_e32 v220, v220, v222
	v_mov_b32_e32 v221, v220
	s_nop 1
	v_permlane16_swap_b32_e32 v220, v221
	v_add_f32_e32 v220, v220, v221
	v_mov_b32_e32 v221, v220
	s_nop 1
	v_permlane32_swap_b32_e32 v220, v221
	v_add_f32_e32 v220, v220, v221
	v_fmamk_f32 v220, v220, 0x3a800000, v161
	v_cmp_gt_f32_e32 vcc, s62, v220
	v_mul_f32_e32 v221, 0x4b800000, v220
	s_nop 0
	v_cndmask_b32_e32 v220, v220, v221, vcc
	v_rsq_f32_e32 v220, v220
	s_nop 0
	v_mul_f32_e32 v221, 0x45800000, v220
	v_cndmask_b32_e32 v220, v220, v221, vcc
	v_add_f32_e32 v224, v224, v225
	v_add_f32_e32 v226, v226, v227
	v_add_f32_e32 v224, v224, v226
	v_mov_b32_e32 v225, v224
	s_nop 1
	v_permlane16_swap_b32_e32 v224, v225
	v_add_f32_e32 v224, v224, v225
	v_mov_b32_e32 v225, v224
	s_nop 1
	v_permlane32_swap_b32_e32 v224, v225
	v_add_f32_e32 v224, v224, v225
	v_fmamk_f32 v224, v224, 0x3a800000, v161
	v_cmp_gt_f32_e32 vcc, s62, v224
	v_mul_f32_e32 v225, 0x4b800000, v224
	s_nop 0
	v_cndmask_b32_e32 v224, v224, v225, vcc
	v_rsq_f32_e32 v224, v224
	s_nop 0
	v_mul_f32_e32 v225, 0x45800000, v224
	v_cndmask_b32_e32 v224, v224, v225, vcc
	v_add_f32_e32 v228, v228, v229
	v_add_f32_e32 v230, v230, v231
	v_add_f32_e32 v228, v228, v230
	v_mov_b32_e32 v229, v228
	s_nop 1
	v_permlane16_swap_b32_e32 v228, v229
	v_add_f32_e32 v228, v228, v229
	v_mov_b32_e32 v229, v228
	s_nop 1
	v_permlane32_swap_b32_e32 v228, v229
	v_add_f32_e32 v228, v228, v229
	v_fmamk_f32 v228, v228, 0x3a800000, v161
	v_cmp_gt_f32_e32 vcc, s62, v228
	v_mul_f32_e32 v229, 0x4b800000, v228
	s_nop 0
	v_cndmask_b32_e32 v228, v228, v229, vcc
	v_rsq_f32_e32 v228, v228
	s_nop 0
	v_mul_f32_e32 v229, 0x45800000, v228
	v_cndmask_b32_e32 v228, v228, v229, vcc
	v_add_f32_e32 v232, v232, v233
	v_add_f32_e32 v234, v234, v235
	v_add_f32_e32 v232, v232, v234
	v_mov_b32_e32 v233, v232
	s_nop 1
	v_permlane16_swap_b32_e32 v232, v233
	v_add_f32_e32 v232, v232, v233
	v_mov_b32_e32 v233, v232
	s_nop 1
	v_permlane32_swap_b32_e32 v232, v233
	v_add_f32_e32 v232, v232, v233
	v_fmamk_f32 v232, v232, 0x3a800000, v161
	v_cmp_gt_f32_e32 vcc, s62, v232
	v_mul_f32_e32 v233, 0x4b800000, v232
	s_nop 0
	v_cndmask_b32_e32 v232, v232, v233, vcc
	v_rsq_f32_e32 v232, v232
	s_nop 0
	v_mul_f32_e32 v233, 0x45800000, v232
	v_cndmask_b32_e32 v232, v232, v233, vcc
	ds_write_b32 v140, v204
	ds_write_b32 v140, v208 offset:4
	ds_write_b32 v140, v212 offset:8
	ds_write_b32 v140, v216 offset:12
	ds_write_b32 v140, v220 offset:16
	ds_write_b32 v140, v224 offset:20
	ds_write_b32 v140, v228 offset:24
	ds_write_b32 v140, v232 offset:28
	s_waitcnt lgkmcnt(0)
	s_branch .LBB0_1599

.LBB0_1605:
	v_bfe_u32 v246, v197, 4, 1
	v_mul_u32_u24_e32 v246, 0x15ff8, v246
	v_mov_b32_e32 v247, 0
	v_lshl_add_u32 v140, s41, 8, v145
	v_ashrrev_i32_e32 v141, 31, v140
	v_lshlrev_b64 v[164:165], 6, v[140:141]
	v_lshl_add_u64 v[164:165], s[66:67], 0, v[164:165]
	v_and_b32_e32 v166, 48, v197
	v_mov_b32_e32 v167, 0
	v_lshl_add_u64 v[164:165], v[164:165], 0, v[166:167]
	s_mov_b64 s[20:21], 0x2000
	v_lshl_add_u64 v[166:167], v[164:165], 0, s[20:21]
	v_lshl_or_b32 v142, s40, 7, v162
	v_ashrrev_i32_e32 v143, 31, v142
	v_lshlrev_b32_e32 v212, 5, v145
	v_add_u32_e32 v212, 0x20000, v212
	ds_read_b128 v[204:207], v212
	ds_read_b128 v[208:211], v212 offset:16
	s_waitcnt lgkmcnt(0)
	v_mov_b32_e32 v144, v204
	v_pk_mul_f32 v[126:127], v[126:127], v[144:145] op_sel_hi:[1,0]
	v_pk_mul_f32 v[122:123], v[122:123], v[144:145] op_sel_hi:[1,0]
	v_mul_f32_e32 v141, 0xbfb8aa3b, v126
	v_exp_f32_e32 v141, v141
	v_pk_mul_f32 v[124:125], v[124:125], v[144:145] op_sel_hi:[1,0]
	v_pk_mul_f32 v[118:119], v[118:119], v[144:145] op_sel_hi:[1,0]
	v_pk_mul_f32 v[114:115], v[114:115], v[144:145] op_sel_hi:[1,0]
	v_add_f32_e32 v141, 1.0, v141
	v_rcp_f32_e32 v164, v141
	v_mul_f32_e32 v141, 0xbfb8aa3b, v127
	v_exp_f32_e32 v141, v141
	v_pk_mul_f32 v[116:117], v[116:117], v[144:145] op_sel_hi:[1,0]
	v_add_f32_e32 v141, 1.0, v141
	v_rcp_f32_e32 v165, v141
	s_nop 0
	v_pk_mul_f32 v[126:127], v[126:127], v[164:165]
	s_nop 0
	v_pk_mul_f32 v[122:123], v[122:123], v[126:127]
	v_pk_mul_f32 v[126:127], v[128:129], v[144:145] op_sel_hi:[1,0]
	s_nop 0
	v_mul_f32_e32 v128, 0xbfb8aa3b, v126
	v_mul_f32_e32 v129, 0xbfb8aa3b, v127
	v_exp_f32_e32 v128, v128
	v_exp_f32_e32 v129, v129
	v_add_f32_e32 v128, 1.0, v128
	v_add_f32_e32 v129, 1.0, v129
	v_rcp_f32_e32 v128, v128
	v_rcp_f32_e32 v129, v129
	s_nop 0
	v_pk_mul_f32 v[126:127], v[126:127], v[128:129]
	s_nop 0
	v_pk_mul_f32 v[124:125], v[124:125], v[126:127]
	v_cvt_pk_bf16_f32 v126, v122, v123
	v_mov_b64_e32 v[122:123], s[8:9]
	v_cvt_pk_bf16_f32 v127, v124, v125
	v_mad_i64_i32 v[128:129], s[20:21], v140, s1, v[122:123]
	v_lshlrev_b64 v[124:125], 1, v[142:143]
	v_lshl_add_u64 v[128:129], v[128:129], 0, v[124:125]
	v_lshl_add_u64 v[244:245], v[128:129], 0, v[246:247]
	v_mov_b32_e32 v236, v126
	v_mov_b32_e32 v237, v127
	v_mul_f32_e32 v126, 0xbfb8aa3b, v118
	v_mul_f32_e32 v127, 0xbfb8aa3b, v119
	v_exp_f32_e32 v126, v126
	v_exp_f32_e32 v127, v127
	v_add_f32_e32 v126, 1.0, v126
	v_add_f32_e32 v127, 1.0, v127
	v_rcp_f32_e32 v126, v126
	v_rcp_f32_e32 v127, v127
	s_nop 0
	v_pk_mul_f32 v[118:119], v[118:119], v[126:127]
	s_nop 0
	v_pk_mul_f32 v[114:115], v[114:115], v[118:119]
	v_pk_mul_f32 v[118:119], v[120:121], v[144:145] op_sel_hi:[1,0]
	v_or_b32_e32 v126, 16, v140
	v_mul_f32_e32 v120, 0xbfb8aa3b, v118
	v_mul_f32_e32 v121, 0xbfb8aa3b, v119
	v_exp_f32_e32 v120, v120
	v_exp_f32_e32 v121, v121
	v_cvt_pk_bf16_f32 v114, v114, v115
	v_ashrrev_i32_e32 v127, 31, v126
	v_add_f32_e32 v120, 1.0, v120
	v_add_f32_e32 v121, 1.0, v121
	v_rcp_f32_e32 v120, v120
	v_rcp_f32_e32 v121, v121
	s_nop 0
	v_pk_mul_f32 v[118:119], v[118:119], v[120:121]
	s_nop 0
	v_pk_mul_f32 v[116:117], v[116:117], v[118:119]
	s_nop 0
	v_cvt_pk_bf16_f32 v115, v116, v117
	v_mov_b32_e32 v240, v114
	v_mov_b32_e32 v241, v115
	v_mov_b32_e32 v114, v205
	v_pk_mul_f32 v[110:111], v[110:111], v[114:115] op_sel_hi:[1,0]
	s_nop 0
	v_mul_f32_e32 v115, 0xbfb8aa3b, v110
	v_exp_f32_e32 v115, v115
	s_nop 0
	v_add_f32_e32 v115, 1.0, v115
	v_rcp_f32_e32 v116, v115
	v_mul_f32_e32 v115, 0xbfb8aa3b, v111
	v_exp_f32_e32 v115, v115
	s_nop 0
	v_add_f32_e32 v115, 1.0, v115
	v_rcp_f32_e32 v117, v115
	v_pk_mul_f32 v[106:107], v[106:107], v[114:115] op_sel_hi:[1,0]
	v_pk_mul_f32 v[108:109], v[108:109], v[114:115] op_sel_hi:[1,0]
	v_pk_mul_f32 v[102:103], v[102:103], v[114:115] op_sel_hi:[1,0]
	v_pk_mul_f32 v[110:111], v[110:111], v[116:117]
	v_pk_mul_f32 v[98:99], v[98:99], v[114:115] op_sel_hi:[1,0]
	v_pk_mul_f32 v[106:107], v[106:107], v[110:111]
	v_pk_mul_f32 v[110:111], v[112:113], v[114:115] op_sel_hi:[1,0]
	v_cvt_pk_bf16_f32 v106, v106, v107
	v_mul_f32_e32 v112, 0xbfb8aa3b, v110
	v_mul_f32_e32 v113, 0xbfb8aa3b, v111
	v_exp_f32_e32 v112, v112
	v_exp_f32_e32 v113, v113
	v_pk_mul_f32 v[100:101], v[100:101], v[114:115] op_sel_hi:[1,0]
	v_add_f32_e32 v112, 1.0, v112
	v_add_f32_e32 v113, 1.0, v113
	v_rcp_f32_e32 v112, v112
	v_rcp_f32_e32 v113, v113
	s_nop 0
	v_pk_mul_f32 v[110:111], v[110:111], v[112:113]
	s_nop 0
	v_pk_mul_f32 v[108:109], v[108:109], v[110:111]
	s_nop 0
	v_cvt_pk_bf16_f32 v107, v108, v109
	v_mad_i64_i32 v[108:109], s[20:21], v126, s1, v[122:123]
	v_lshl_add_u64 v[108:109], v[108:109], 0, v[124:125]
	v_mov_b32_e32 v238, v106
	v_mov_b32_e32 v239, v107
	s_nop 1
	v_permlane16_swap_b32_e32 v236, v238
	v_permlane16_swap_b32_e32 v237, v239
	global_store_dwordx4 v[244:245], v[236:239], off
	v_mul_f32_e32 v106, 0xbfb8aa3b, v102
	v_mul_f32_e32 v107, 0xbfb8aa3b, v103
	v_exp_f32_e32 v106, v106
	v_exp_f32_e32 v107, v107
	v_add_f32_e32 v106, 1.0, v106
	v_add_f32_e32 v107, 1.0, v107
	v_rcp_f32_e32 v106, v106
	v_rcp_f32_e32 v107, v107
	s_nop 0
	v_pk_mul_f32 v[102:103], v[102:103], v[106:107]
	s_nop 0
	v_pk_mul_f32 v[98:99], v[98:99], v[102:103]
	v_pk_mul_f32 v[102:103], v[104:105], v[114:115] op_sel_hi:[1,0]
	v_or_b32_e32 v106, 32, v140
	v_mul_f32_e32 v104, 0xbfb8aa3b, v102
	v_mul_f32_e32 v105, 0xbfb8aa3b, v103
	v_exp_f32_e32 v104, v104
	v_exp_f32_e32 v105, v105
	v_cvt_pk_bf16_f32 v98, v98, v99
	v_ashrrev_i32_e32 v107, 31, v106
	v_add_f32_e32 v104, 1.0, v104
	v_add_f32_e32 v105, 1.0, v105
	v_rcp_f32_e32 v104, v104
	v_rcp_f32_e32 v105, v105
	s_nop 0
	v_pk_mul_f32 v[102:103], v[102:103], v[104:105]
	s_nop 0
	v_pk_mul_f32 v[100:101], v[100:101], v[102:103]
	s_nop 0
	v_cvt_pk_bf16_f32 v99, v100, v101
	v_mov_b32_e32 v242, v98
	v_mov_b32_e32 v243, v99
	s_nop 1
	v_permlane16_swap_b32_e32 v240, v242
	v_permlane16_swap_b32_e32 v241, v243
	global_store_dwordx4 v[244:245], v[240:243], off offset:128
	v_mov_b32_e32 v98, v206
	v_pk_mul_f32 v[94:95], v[94:95], v[98:99] op_sel_hi:[1,0]
	s_nop 0
	v_mul_f32_e32 v99, 0xbfb8aa3b, v94
	v_exp_f32_e32 v99, v99
	s_nop 0
	v_add_f32_e32 v99, 1.0, v99
	v_rcp_f32_e32 v100, v99
	v_mul_f32_e32 v99, 0xbfb8aa3b, v95
	v_exp_f32_e32 v99, v99
	s_nop 0
	v_add_f32_e32 v99, 1.0, v99
	v_rcp_f32_e32 v101, v99
	v_pk_mul_f32 v[90:91], v[90:91], v[98:99] op_sel_hi:[1,0]
	v_pk_mul_f32 v[92:93], v[92:93], v[98:99] op_sel_hi:[1,0]
	v_pk_mul_f32 v[86:87], v[86:87], v[98:99] op_sel_hi:[1,0]
	v_pk_mul_f32 v[94:95], v[94:95], v[100:101]
	v_pk_mul_f32 v[82:83], v[82:83], v[98:99] op_sel_hi:[1,0]
	v_pk_mul_f32 v[90:91], v[90:91], v[94:95]
	v_pk_mul_f32 v[94:95], v[96:97], v[98:99] op_sel_hi:[1,0]
	v_cvt_pk_bf16_f32 v90, v90, v91
	v_mul_f32_e32 v96, 0xbfb8aa3b, v94
	v_mul_f32_e32 v97, 0xbfb8aa3b, v95
	v_exp_f32_e32 v96, v96
	v_exp_f32_e32 v97, v97
	v_pk_mul_f32 v[84:85], v[84:85], v[98:99] op_sel_hi:[1,0]
	v_add_f32_e32 v96, 1.0, v96
	v_add_f32_e32 v97, 1.0, v97
	v_rcp_f32_e32 v96, v96
	v_rcp_f32_e32 v97, v97
	s_nop 0
	v_pk_mul_f32 v[94:95], v[94:95], v[96:97]
	s_nop 0
	v_pk_mul_f32 v[92:93], v[92:93], v[94:95]
	s_nop 0
	v_cvt_pk_bf16_f32 v91, v92, v93
	v_mad_i64_i32 v[92:93], s[20:21], v106, s1, v[122:123]
	v_lshl_add_u64 v[92:93], v[92:93], 0, v[124:125]
	v_lshl_add_u64 v[244:245], v[92:93], 0, v[246:247]
	v_mov_b32_e32 v236, v90
	v_mov_b32_e32 v237, v91
	v_mul_f32_e32 v90, 0xbfb8aa3b, v86
	v_mul_f32_e32 v91, 0xbfb8aa3b, v87
	v_exp_f32_e32 v90, v90
	v_exp_f32_e32 v91, v91
	v_add_f32_e32 v90, 1.0, v90
	v_add_f32_e32 v91, 1.0, v91
	v_rcp_f32_e32 v90, v90
	v_rcp_f32_e32 v91, v91
	s_nop 0
	v_pk_mul_f32 v[86:87], v[86:87], v[90:91]
	s_nop 0
	v_pk_mul_f32 v[82:83], v[82:83], v[86:87]
	v_pk_mul_f32 v[86:87], v[88:89], v[98:99] op_sel_hi:[1,0]
	v_or_b32_e32 v90, 48, v140
	v_mul_f32_e32 v88, 0xbfb8aa3b, v86
	v_mul_f32_e32 v89, 0xbfb8aa3b, v87
	v_exp_f32_e32 v88, v88
	v_exp_f32_e32 v89, v89
	v_cvt_pk_bf16_f32 v82, v82, v83
	v_ashrrev_i32_e32 v91, 31, v90
	v_add_f32_e32 v88, 1.0, v88
	v_add_f32_e32 v89, 1.0, v89
	v_rcp_f32_e32 v88, v88
	v_rcp_f32_e32 v89, v89
	s_nop 0
	v_pk_mul_f32 v[86:87], v[86:87], v[88:89]
	s_nop 0
	v_pk_mul_f32 v[84:85], v[84:85], v[86:87]
	s_nop 0
	v_cvt_pk_bf16_f32 v83, v84, v85
	v_mov_b32_e32 v240, v82
	v_mov_b32_e32 v241, v83
	v_mov_b32_e32 v82, v207
	v_pk_mul_f32 v[78:79], v[78:79], v[82:83] op_sel_hi:[1,0]
	s_nop 0
	v_mul_f32_e32 v83, 0xbfb8aa3b, v78
	v_exp_f32_e32 v83, v83
	s_nop 0
	v_add_f32_e32 v83, 1.0, v83
	v_rcp_f32_e32 v84, v83
	v_mul_f32_e32 v83, 0xbfb8aa3b, v79
	v_exp_f32_e32 v83, v83
	s_nop 0
	v_add_f32_e32 v83, 1.0, v83
	v_rcp_f32_e32 v85, v83
	v_pk_mul_f32 v[74:75], v[74:75], v[82:83] op_sel_hi:[1,0]
	v_pk_mul_f32 v[76:77], v[76:77], v[82:83] op_sel_hi:[1,0]
	v_pk_mul_f32 v[70:71], v[70:71], v[82:83] op_sel_hi:[1,0]
	v_pk_mul_f32 v[78:79], v[78:79], v[84:85]
	v_pk_mul_f32 v[66:67], v[66:67], v[82:83] op_sel_hi:[1,0]
	v_pk_mul_f32 v[74:75], v[74:75], v[78:79]
	v_pk_mul_f32 v[78:79], v[80:81], v[82:83] op_sel_hi:[1,0]
	v_cvt_pk_bf16_f32 v74, v74, v75
	v_mul_f32_e32 v80, 0xbfb8aa3b, v78
	v_mul_f32_e32 v81, 0xbfb8aa3b, v79
	v_exp_f32_e32 v80, v80
	v_exp_f32_e32 v81, v81
	v_pk_mul_f32 v[68:69], v[68:69], v[82:83] op_sel_hi:[1,0]
	v_add_f32_e32 v80, 1.0, v80
	v_add_f32_e32 v81, 1.0, v81
	v_rcp_f32_e32 v80, v80
	v_rcp_f32_e32 v81, v81
	s_nop 0
	v_pk_mul_f32 v[78:79], v[78:79], v[80:81]
	s_nop 0
	v_pk_mul_f32 v[76:77], v[76:77], v[78:79]
	s_nop 0
	v_cvt_pk_bf16_f32 v75, v76, v77
	v_mad_i64_i32 v[76:77], s[20:21], v90, s1, v[122:123]
	v_lshl_add_u64 v[76:77], v[76:77], 0, v[124:125]
	v_mov_b32_e32 v238, v74
	v_mov_b32_e32 v239, v75
	s_nop 1
	v_permlane16_swap_b32_e32 v236, v238
	v_permlane16_swap_b32_e32 v237, v239
	global_store_dwordx4 v[244:245], v[236:239], off
	v_mul_f32_e32 v74, 0xbfb8aa3b, v70
	v_mul_f32_e32 v75, 0xbfb8aa3b, v71
	v_exp_f32_e32 v74, v74
	v_exp_f32_e32 v75, v75
	v_add_f32_e32 v74, 1.0, v74
	v_add_f32_e32 v75, 1.0, v75
	v_rcp_f32_e32 v74, v74
	v_rcp_f32_e32 v75, v75
	s_nop 0
	v_pk_mul_f32 v[70:71], v[70:71], v[74:75]
	s_nop 0
	v_pk_mul_f32 v[66:67], v[66:67], v[70:71]
	v_pk_mul_f32 v[70:71], v[72:73], v[82:83] op_sel_hi:[1,0]
	v_add_u32_e32 v74, 0x80, v140
	v_mul_f32_e32 v72, 0xbfb8aa3b, v70
	v_mul_f32_e32 v73, 0xbfb8aa3b, v71
	v_exp_f32_e32 v72, v72
	v_exp_f32_e32 v73, v73
	v_cvt_pk_bf16_f32 v66, v66, v67
	v_ashrrev_i32_e32 v75, 31, v74
	v_add_f32_e32 v72, 1.0, v72
	v_add_f32_e32 v73, 1.0, v73
	v_rcp_f32_e32 v72, v72
	v_rcp_f32_e32 v73, v73
	s_nop 0
	v_pk_mul_f32 v[70:71], v[70:71], v[72:73]
	s_nop 0
	v_pk_mul_f32 v[68:69], v[68:69], v[70:71]
	s_nop 0
	v_cvt_pk_bf16_f32 v67, v68, v69
	v_mov_b32_e32 v242, v66
	v_mov_b32_e32 v243, v67
	s_nop 1
	v_permlane16_swap_b32_e32 v240, v242
	v_permlane16_swap_b32_e32 v241, v243
	global_store_dwordx4 v[244:245], v[240:243], off offset:128
	v_mov_b32_e32 v66, v208
	v_pk_mul_f32 v[62:63], v[62:63], v[66:67] op_sel_hi:[1,0]
	s_nop 0
	v_mul_f32_e32 v67, 0xbfb8aa3b, v62
	v_exp_f32_e32 v67, v67
	s_nop 0
	v_add_f32_e32 v67, 1.0, v67
	v_rcp_f32_e32 v68, v67
	v_mul_f32_e32 v67, 0xbfb8aa3b, v63
	v_exp_f32_e32 v67, v67
	s_nop 0
	v_add_f32_e32 v67, 1.0, v67
	v_rcp_f32_e32 v69, v67
	v_pk_mul_f32 v[58:59], v[58:59], v[66:67] op_sel_hi:[1,0]
	v_pk_mul_f32 v[60:61], v[60:61], v[66:67] op_sel_hi:[1,0]
	v_pk_mul_f32 v[54:55], v[54:55], v[66:67] op_sel_hi:[1,0]
	v_pk_mul_f32 v[62:63], v[62:63], v[68:69]
	v_pk_mul_f32 v[50:51], v[50:51], v[66:67] op_sel_hi:[1,0]
	v_pk_mul_f32 v[58:59], v[58:59], v[62:63]
	v_pk_mul_f32 v[62:63], v[64:65], v[66:67] op_sel_hi:[1,0]
	v_cvt_pk_bf16_f32 v58, v58, v59
	v_mul_f32_e32 v64, 0xbfb8aa3b, v62
	v_mul_f32_e32 v65, 0xbfb8aa3b, v63
	v_exp_f32_e32 v64, v64
	v_exp_f32_e32 v65, v65
	v_pk_mul_f32 v[52:53], v[52:53], v[66:67] op_sel_hi:[1,0]
	v_add_f32_e32 v64, 1.0, v64
	v_add_f32_e32 v65, 1.0, v65
	v_rcp_f32_e32 v64, v64
	v_rcp_f32_e32 v65, v65
	s_nop 0
	v_pk_mul_f32 v[62:63], v[62:63], v[64:65]
	s_nop 0
	v_pk_mul_f32 v[60:61], v[60:61], v[62:63]
	s_nop 0
	v_cvt_pk_bf16_f32 v59, v60, v61
	v_mad_i64_i32 v[60:61], s[20:21], v74, s1, v[122:123]
	v_lshl_add_u64 v[60:61], v[60:61], 0, v[124:125]
	v_lshl_add_u64 v[244:245], v[60:61], 0, v[246:247]
	v_mov_b32_e32 v236, v58
	v_mov_b32_e32 v237, v59
	v_mul_f32_e32 v58, 0xbfb8aa3b, v54
	v_mul_f32_e32 v59, 0xbfb8aa3b, v55
	v_exp_f32_e32 v58, v58
	v_exp_f32_e32 v59, v59
	v_add_f32_e32 v58, 1.0, v58
	v_add_f32_e32 v59, 1.0, v59
	v_rcp_f32_e32 v58, v58
	v_rcp_f32_e32 v59, v59
	s_nop 0
	v_pk_mul_f32 v[54:55], v[54:55], v[58:59]
	s_nop 0
	v_pk_mul_f32 v[50:51], v[50:51], v[54:55]
	v_pk_mul_f32 v[54:55], v[56:57], v[66:67] op_sel_hi:[1,0]
	v_add_u32_e32 v58, 0x90, v140
	v_mul_f32_e32 v56, 0xbfb8aa3b, v54
	v_mul_f32_e32 v57, 0xbfb8aa3b, v55
	v_exp_f32_e32 v56, v56
	v_exp_f32_e32 v57, v57
	v_cvt_pk_bf16_f32 v50, v50, v51
	v_ashrrev_i32_e32 v59, 31, v58
	v_add_f32_e32 v56, 1.0, v56
	v_add_f32_e32 v57, 1.0, v57
	v_rcp_f32_e32 v56, v56
	v_rcp_f32_e32 v57, v57
	s_nop 0
	v_pk_mul_f32 v[54:55], v[54:55], v[56:57]
	s_nop 0
	v_pk_mul_f32 v[52:53], v[52:53], v[54:55]
	s_nop 0
	v_cvt_pk_bf16_f32 v51, v52, v53
	v_mov_b32_e32 v240, v50
	v_mov_b32_e32 v241, v51
	v_mov_b32_e32 v50, v209
	v_pk_mul_f32 v[46:47], v[46:47], v[50:51] op_sel_hi:[1,0]
	s_nop 0
	v_mul_f32_e32 v51, 0xbfb8aa3b, v46
	v_exp_f32_e32 v51, v51
	s_nop 0
	v_add_f32_e32 v51, 1.0, v51
	v_rcp_f32_e32 v52, v51
	v_mul_f32_e32 v51, 0xbfb8aa3b, v47
	v_exp_f32_e32 v51, v51
	s_nop 0
	v_add_f32_e32 v51, 1.0, v51
	v_rcp_f32_e32 v53, v51
	v_pk_mul_f32 v[42:43], v[42:43], v[50:51] op_sel_hi:[1,0]
	v_pk_mul_f32 v[44:45], v[44:45], v[50:51] op_sel_hi:[1,0]
	v_pk_mul_f32 v[38:39], v[38:39], v[50:51] op_sel_hi:[1,0]
	v_pk_mul_f32 v[46:47], v[46:47], v[52:53]
	v_pk_mul_f32 v[34:35], v[34:35], v[50:51] op_sel_hi:[1,0]
	v_pk_mul_f32 v[42:43], v[42:43], v[46:47]
	v_pk_mul_f32 v[46:47], v[48:49], v[50:51] op_sel_hi:[1,0]
	v_cvt_pk_bf16_f32 v42, v42, v43
	v_mul_f32_e32 v48, 0xbfb8aa3b, v46
	v_mul_f32_e32 v49, 0xbfb8aa3b, v47
	v_exp_f32_e32 v48, v48
	v_exp_f32_e32 v49, v49
	v_pk_mul_f32 v[36:37], v[36:37], v[50:51] op_sel_hi:[1,0]
	v_add_f32_e32 v48, 1.0, v48
	v_add_f32_e32 v49, 1.0, v49
	v_rcp_f32_e32 v48, v48
	v_rcp_f32_e32 v49, v49
	s_nop 0
	v_pk_mul_f32 v[46:47], v[46:47], v[48:49]
	s_nop 0
	v_pk_mul_f32 v[44:45], v[44:45], v[46:47]
	s_nop 0
	v_cvt_pk_bf16_f32 v43, v44, v45
	v_mad_i64_i32 v[44:45], s[20:21], v58, s1, v[122:123]
	v_lshl_add_u64 v[44:45], v[44:45], 0, v[124:125]
	v_mov_b32_e32 v238, v42
	v_mov_b32_e32 v239, v43
	s_nop 1
	v_permlane16_swap_b32_e32 v236, v238
	v_permlane16_swap_b32_e32 v237, v239
	global_store_dwordx4 v[244:245], v[236:239], off
	v_mul_f32_e32 v42, 0xbfb8aa3b, v38
	v_mul_f32_e32 v43, 0xbfb8aa3b, v39
	v_exp_f32_e32 v42, v42
	v_exp_f32_e32 v43, v43
	v_add_f32_e32 v42, 1.0, v42
	v_add_f32_e32 v43, 1.0, v43
	v_rcp_f32_e32 v42, v42
	v_rcp_f32_e32 v43, v43
	s_nop 0
	v_pk_mul_f32 v[38:39], v[38:39], v[42:43]
	s_nop 0
	v_pk_mul_f32 v[34:35], v[34:35], v[38:39]
	v_pk_mul_f32 v[38:39], v[40:41], v[50:51] op_sel_hi:[1,0]
	v_add_u32_e32 v42, 0xa0, v140
	v_mul_f32_e32 v40, 0xbfb8aa3b, v38
	v_mul_f32_e32 v41, 0xbfb8aa3b, v39
	v_exp_f32_e32 v40, v40
	v_exp_f32_e32 v41, v41
	v_cvt_pk_bf16_f32 v34, v34, v35
	v_ashrrev_i32_e32 v43, 31, v42
	v_add_f32_e32 v40, 1.0, v40
	v_add_f32_e32 v41, 1.0, v41
	v_rcp_f32_e32 v40, v40
	v_rcp_f32_e32 v41, v41
	s_nop 0
	v_pk_mul_f32 v[38:39], v[38:39], v[40:41]
	s_nop 0
	v_pk_mul_f32 v[36:37], v[36:37], v[38:39]
	s_nop 0
	v_cvt_pk_bf16_f32 v35, v36, v37
	v_mov_b32_e32 v242, v34
	v_mov_b32_e32 v243, v35
	s_nop 1
	v_permlane16_swap_b32_e32 v240, v242
	v_permlane16_swap_b32_e32 v241, v243
	global_store_dwordx4 v[244:245], v[240:243], off offset:128
	v_mov_b32_e32 v34, v210
	v_pk_mul_f32 v[30:31], v[30:31], v[34:35] op_sel_hi:[1,0]
	s_nop 0
	v_mul_f32_e32 v35, 0xbfb8aa3b, v30
	v_exp_f32_e32 v35, v35
	s_nop 0
	v_add_f32_e32 v35, 1.0, v35
	v_rcp_f32_e32 v36, v35
	v_mul_f32_e32 v35, 0xbfb8aa3b, v31
	v_exp_f32_e32 v35, v35
	s_nop 0
	v_add_f32_e32 v35, 1.0, v35
	v_rcp_f32_e32 v37, v35
	v_pk_mul_f32 v[26:27], v[26:27], v[34:35] op_sel_hi:[1,0]
	v_pk_mul_f32 v[28:29], v[28:29], v[34:35] op_sel_hi:[1,0]
	v_pk_mul_f32 v[22:23], v[22:23], v[34:35] op_sel_hi:[1,0]
	v_pk_mul_f32 v[30:31], v[30:31], v[36:37]
	v_pk_mul_f32 v[18:19], v[18:19], v[34:35] op_sel_hi:[1,0]
	v_pk_mul_f32 v[26:27], v[26:27], v[30:31]
	v_pk_mul_f32 v[30:31], v[32:33], v[34:35] op_sel_hi:[1,0]
	v_cvt_pk_bf16_f32 v26, v26, v27
	v_mul_f32_e32 v32, 0xbfb8aa3b, v30
	v_mul_f32_e32 v33, 0xbfb8aa3b, v31
	v_exp_f32_e32 v32, v32
	v_exp_f32_e32 v33, v33
	v_pk_mul_f32 v[20:21], v[20:21], v[34:35] op_sel_hi:[1,0]
	v_add_f32_e32 v32, 1.0, v32
	v_add_f32_e32 v33, 1.0, v33
	v_rcp_f32_e32 v32, v32
	v_rcp_f32_e32 v33, v33
	s_nop 0
	v_pk_mul_f32 v[30:31], v[30:31], v[32:33]
	s_nop 0
	v_pk_mul_f32 v[28:29], v[28:29], v[30:31]
	s_nop 0
	v_cvt_pk_bf16_f32 v27, v28, v29
	v_mad_i64_i32 v[28:29], s[20:21], v42, s1, v[122:123]
	v_lshl_add_u64 v[28:29], v[28:29], 0, v[124:125]
	v_lshl_add_u64 v[244:245], v[28:29], 0, v[246:247]
	v_mov_b32_e32 v236, v26
	v_mov_b32_e32 v237, v27
	v_mul_f32_e32 v26, 0xbfb8aa3b, v22
	v_mul_f32_e32 v27, 0xbfb8aa3b, v23
	v_exp_f32_e32 v26, v26
	v_exp_f32_e32 v27, v27
	v_add_f32_e32 v26, 1.0, v26
	v_add_f32_e32 v27, 1.0, v27
	v_rcp_f32_e32 v26, v26
	v_rcp_f32_e32 v27, v27
	s_nop 0
	v_pk_mul_f32 v[22:23], v[22:23], v[26:27]
	s_nop 0
	v_pk_mul_f32 v[18:19], v[18:19], v[22:23]
	v_pk_mul_f32 v[22:23], v[24:25], v[34:35] op_sel_hi:[1,0]
	v_add_u32_e32 v26, 0xb0, v140
	v_mul_f32_e32 v24, 0xbfb8aa3b, v22
	v_mul_f32_e32 v25, 0xbfb8aa3b, v23
	v_exp_f32_e32 v24, v24
	v_exp_f32_e32 v25, v25
	v_cvt_pk_bf16_f32 v18, v18, v19
	v_ashrrev_i32_e32 v27, 31, v26
	v_add_f32_e32 v24, 1.0, v24
	v_add_f32_e32 v25, 1.0, v25
	v_rcp_f32_e32 v24, v24
	v_rcp_f32_e32 v25, v25
	s_nop 0
	v_pk_mul_f32 v[22:23], v[22:23], v[24:25]
	s_nop 0
	v_pk_mul_f32 v[20:21], v[20:21], v[22:23]
	s_nop 0
	v_cvt_pk_bf16_f32 v19, v20, v21
	v_mov_b32_e32 v240, v18
	v_mov_b32_e32 v241, v19
	v_mov_b32_e32 v18, v211
	v_pk_mul_f32 v[14:15], v[14:15], v[18:19] op_sel_hi:[1,0]
	s_andn2_b64 vcc, exec, s[6:7]
	v_mul_f32_e32 v19, 0xbfb8aa3b, v14
	v_exp_f32_e32 v19, v19
	s_nop 0
	v_add_f32_e32 v19, 1.0, v19
	v_rcp_f32_e32 v20, v19
	v_mul_f32_e32 v19, 0xbfb8aa3b, v15
	v_exp_f32_e32 v19, v19
	s_nop 0
	v_add_f32_e32 v19, 1.0, v19
	v_rcp_f32_e32 v21, v19
	v_pk_mul_f32 v[10:11], v[10:11], v[18:19] op_sel_hi:[1,0]
	v_pk_mul_f32 v[12:13], v[12:13], v[18:19] op_sel_hi:[1,0]
	v_pk_mul_f32 v[6:7], v[6:7], v[18:19] op_sel_hi:[1,0]
	v_pk_mul_f32 v[14:15], v[14:15], v[20:21]
	v_pk_mul_f32 v[2:3], v[2:3], v[18:19] op_sel_hi:[1,0]
	v_pk_mul_f32 v[10:11], v[10:11], v[14:15]
	v_pk_mul_f32 v[14:15], v[16:17], v[18:19] op_sel_hi:[1,0]
	v_cvt_pk_bf16_f32 v10, v10, v11
	v_mul_f32_e32 v16, 0xbfb8aa3b, v14
	v_mul_f32_e32 v17, 0xbfb8aa3b, v15
	v_exp_f32_e32 v16, v16
	v_exp_f32_e32 v17, v17
	v_pk_mul_f32 v[4:5], v[4:5], v[18:19] op_sel_hi:[1,0]
	v_add_f32_e32 v16, 1.0, v16
	v_add_f32_e32 v17, 1.0, v17
	v_rcp_f32_e32 v16, v16
	v_rcp_f32_e32 v17, v17
	s_nop 0
	v_pk_mul_f32 v[14:15], v[14:15], v[16:17]
	s_nop 0
	v_pk_mul_f32 v[12:13], v[12:13], v[14:15]
	s_nop 0
	v_cvt_pk_bf16_f32 v11, v12, v13
	v_mad_i64_i32 v[12:13], s[20:21], v26, s1, v[122:123]
	v_lshl_add_u64 v[12:13], v[12:13], 0, v[124:125]
	v_mov_b32_e32 v238, v10
	v_mov_b32_e32 v239, v11
	s_nop 1
	v_permlane16_swap_b32_e32 v236, v238
	v_permlane16_swap_b32_e32 v237, v239
	global_store_dwordx4 v[244:245], v[236:239], off
	v_mul_f32_e32 v10, 0xbfb8aa3b, v6
	v_mul_f32_e32 v11, 0xbfb8aa3b, v7
	v_exp_f32_e32 v10, v10
	v_exp_f32_e32 v11, v11
	s_mov_b64 s[20:21], -1
	v_add_f32_e32 v10, 1.0, v10
	v_add_f32_e32 v11, 1.0, v11
	v_rcp_f32_e32 v10, v10
	v_rcp_f32_e32 v11, v11
	s_nop 0
	v_pk_mul_f32 v[6:7], v[6:7], v[10:11]
	s_nop 0
	v_pk_mul_f32 v[2:3], v[2:3], v[6:7]
	v_pk_mul_f32 v[6:7], v[8:9], v[18:19] op_sel_hi:[1,0]
	v_cvt_pk_bf16_f32 v2, v2, v3
	v_mul_f32_e32 v8, 0xbfb8aa3b, v6
	v_mul_f32_e32 v9, 0xbfb8aa3b, v7
	v_exp_f32_e32 v8, v8
	v_exp_f32_e32 v9, v9
	v_add_f32_e32 v8, 1.0, v8
	v_add_f32_e32 v9, 1.0, v9
	v_rcp_f32_e32 v8, v8
	v_rcp_f32_e32 v9, v9
	s_nop 0
	v_pk_mul_f32 v[6:7], v[6:7], v[8:9]
	s_nop 0
	v_pk_mul_f32 v[4:5], v[4:5], v[6:7]
	s_nop 0
	v_cvt_pk_bf16_f32 v3, v4, v5
	v_mov_b32_e32 v242, v2
	v_mov_b32_e32 v243, v3
	s_nop 1
	v_permlane16_swap_b32_e32 v240, v242
	v_permlane16_swap_b32_e32 v241, v243
	global_store_dwordx4 v[244:245], v[240:243], off offset:128
	s_cbranch_vccnz .LBB0_1598
	s_andn2_b64 vcc, exec, s[4:5]
	s_cbranch_vccnz .LBB0_1597
	s_barrier
	s_branch .LBB0_1597
